# hand-written attention-A round loop: 2 rounds of 8 query rows, rows interleaved between SIMD partner waves, paired tiles, early gate loads
# speedup vs baseline: 1.0075x; 1.0075x over previous
.LBB0_264:
	s_or_b64 exec, exec, s[4:5]
	s_ashr_i32 s4, s52, 7
	s_bfe_u32 s24, s52, 0x40003
	s_lshl_b32 s18, s24, 14
	s_ashr_i32 s5, s4, 31
	s_or_b32 s6, s18, 0x40000
	s_lshl_b64 s[8:9], s[4:5], 13
	s_add_u32 s6, s8, s6
	s_addc_u32 s7, s9, 0
	s_lshl_b64 s[14:15], s[4:5], 20
	s_lshl_b32 s4, s52, 4
	s_lshl_b64 s[6:7], s[6:7], 7
	s_lshl_b32 s13, s24, 21
	s_and_b32 s12, s4, 0x70
	s_add_u32 s4, s10, s6
	s_addc_u32 s5, s11, s7
	s_add_u32 s0, s0, s13
	s_addc_u32 s1, s1, 0
	s_add_u32 s0, s0, s14
	s_waitcnt lgkmcnt(0)
	v_sub_u32_e64 v2, s12, 4 clamp
	s_addc_u32 s1, s1, s15
	s_or_b32 s6, s12, 10
	v_lshlrev_b32_e32 v6, 13, v2
	v_or_b32_e32 v2, 1, v2
	v_mov_b32_e32 v5, v0
	s_barrier
	v_min_u32_e32 v2, s6, v2
	v_lshlrev_b32_e32 v8, 13, v2
	v_readfirstlane_b32 s6, v5
	s_ashr_i32 s7, s6, 6
	v_and_b32_e32 v2, 63, v5
	s_lshl_b32 s13, s7, 4
	s_and_b32 s29, s13, 48
	v_lshlrev_b32_e32 v254, 4, v2
	s_lshl_b32 s13, s7, 2
	v_and_b32_e32 v3, 7, v5
	s_lshl_b32 s15, s7, 10
	v_and_b32_e32 v2, 0x380, v254
	v_bfe_u32 v10, v5, 4, 1
	s_and_b32 s13, s13, 4
	s_lshr_b32 s6, s6, 7
	v_or_b32_e32 v2, s15, v2
	v_lshrrev_b32_e32 v4, 4, v5
	v_bitop3_b32 v3, s13, v3, v10 bitop3:0x36
	s_and_b32 s6, s6, 2
	v_lshl_or_b32 v10, v3, 4, v2
	v_lshl_or_b32 v3, v4, 2, s6
	v_sub_u32_e32 v3, v5, v3
	s_movk_i32 s19, 0x70
	v_lshlrev_b32_e32 v3, 4, v3
	s_lshl_b32 s6, s7, 13
	v_and_or_b32 v12, v3, s19, v2
	s_add_i32 s19, s6, 0
	s_and_b32 s14, s7, -4
	s_add_i32 s13, s19, 0x10000
	s_add_i32 s6, s14, s12
	s_or_b32 s8, s8, s29
	s_add_u32 s26, s8, s18
	s_addc_u32 s27, s9, 0
	s_lshl_b32 s28, s6, 6
	s_ashr_i32 s7, s28, 31
	s_add_u32 s6, s26, s28
	s_addc_u32 s7, s27, s7
	v_and_b32_e32 v231, 15, v5
	s_lshl_b64 s[6:7], s[6:7], 7
	v_mov_b32_e32 v7, 0
	v_bfe_u32 v251, v5, 4, 2
	v_lshlrev_b32_e32 v2, 7, v231
	s_add_u32 s6, s10, s6
	v_lshl_or_b32 v2, v251, 5, v2
	v_mov_b32_e32 v3, v7
	s_addc_u32 s7, s11, s7
	s_mov_b32 m0, s13
	v_lshl_add_u64 v[14:15], s[6:7], 0, v[2:3]
	s_nop 0
	s_or_b32 s6, s28, 64
	s_add_i32 m0, s19, 0x10400
	s_ashr_i32 s7, s6, 31
	s_add_u32 s6, s26, s6
	s_addc_u32 s7, s27, s7
	s_lshl_b64 s[6:7], s[6:7], 7
	v_lshl_add_u64 v[14:15], v[14:15], 0, 16
	s_add_u32 s6, s10, s6
	s_nop 0
	s_addc_u32 s7, s11, s7
	s_add_i32 m0, s19, 0x10800
	v_lshl_add_u64 v[14:15], s[6:7], 0, v[2:3]
	s_nop 0
	s_or_b32 s6, s28, 0x80
	s_add_i32 m0, s19, 0x10c00
	s_ashr_i32 s7, s6, 31
	s_add_u32 s6, s26, s6
	s_addc_u32 s7, s27, s7
	s_lshl_b64 s[6:7], s[6:7], 7
	v_lshl_add_u64 v[14:15], v[14:15], 0, 16
	s_add_u32 s6, s10, s6
	s_nop 0
	s_addc_u32 s7, s11, s7
	s_add_i32 m0, s19, 0x11000
	v_lshl_add_u64 v[14:15], s[6:7], 0, v[2:3]
	s_nop 0
	s_or_b32 s6, s28, 0xc0
	s_add_i32 m0, s19, 0x11400
	s_ashr_i32 s7, s6, 31
	s_add_u32 s6, s26, s6
	s_addc_u32 s7, s27, s7
	s_lshl_b64 s[6:7], s[6:7], 7
	s_add_u32 s6, s10, s6
	v_lshl_add_u64 v[14:15], v[14:15], 0, 16
	s_addc_u32 s7, s11, s7
	v_mov_b32_e32 v11, v7
	s_nop 0
	v_lshl_add_u64 v[14:15], s[6:7], 0, v[2:3]
	s_add_i32 m0, s19, 0x11800
	v_mov_b32_e32 v13, v7
	s_nop 0
	v_lshl_add_u64 v[14:15], v[14:15], 0, 16
	s_add_i32 m0, s19, 0x11c00
	v_lshl_add_u64 v[202:203], s[4:5], 0, v[10:11]
	s_add_i32 s15, s15, 0
	s_nop 0
	v_lshl_add_u64 v[204:205], s[0:1], 0, v[12:13]
	v_lshl_add_u64 v[10:11], v[202:203], 0, v[6:7]
	s_mov_b32 m0, s15
	v_mov_b32_e32 v9, v7
	s_nop 0
	v_lshl_add_u64 v[6:7], v[204:205], 0, v[6:7]
	s_add_i32 m0, s15, 0x2000
	s_movk_i32 s0, 0x1e0
	s_nop 0
	v_lshl_add_u64 v[6:7], v[202:203], 0, v[8:9]
	s_add_i32 m0, s15, 0x4000
	v_cmp_gt_i32_e32 vcc, s0, v5
	s_nop 0
	v_lshl_add_u64 v[6:7], v[204:205], 0, v[8:9]
	s_add_i32 m0, s15, 0x6000
	s_nop 0
	s_nop 0
	s_and_saveexec_b64 s[4:5], vcc
	s_cbranch_execz .LBB0_269
	s_mul_i32 s0, s24, 0x1d1
	v_and_b32_e32 v4, 31, v5
	v_lshl_add_u32 v6, v5, 2, 0
	v_cmp_ne_u32_e32 vcc, 31, v4
	v_add_u32_e32 v4, s0, v4
	v_add_u32_e32 v6, 0x20000, v6
	s_mov_b64 s[6:7], 0
	s_movk_i32 s18, 0xffdf
	v_mov_b32_e32 v7, v5
	s_branch .LBB0_267

.LBB0_269:
	s_or_b64 exec, exec, s[4:5]
	s_add_u32 s18, s56, 0xc400000
	s_addc_u32 s19, s57, 0
	s_or_b32 s0, s12, 11
	s_min_u32 s0, s0, 0x78
	s_add_i32 s0, s0, 7
	s_lshl_b32 s1, s24, 7
	s_add_u32 s20, s20, s1
	s_addc_u32 s21, s21, 0
	s_add_u32 s24, s18, s1
	v_sub_u32_e64 v4, s29, 8 clamp
	s_addc_u32 s25, s19, 0
	s_or_b32 s1, s12, 4
	v_min_u32_e32 v4, 32, v4
	v_or_b32_e32 v8, s29, v231
	s_min_u32 s1, s1, s0
	v_sub_u32_e64 v9, v8, 8 clamp
	v_lshl_add_u32 v10, v251, 3, v4
	s_lshl_b32 s22, s1, 13
	s_or_b32 s1, s12, 5
	v_min_u32_e32 v9, 48, v9
	v_sub_u32_e32 v12, v10, v8
	s_min_u32 s0, s1, s0
	v_add_u32_e32 v11, 16, v9
	v_max_i32_e32 v12, -15, v12
	s_lshl_b32 s4, s0, 13
	v_cmp_ge_u32_e32 vcc, v10, v9
	v_cmp_lt_u32_e64 s[0:1], v10, v11
	v_add_u32_e32 v12, 15, v12
	v_min_u32_e32 v12, 30, v12
	s_and_b64 vcc, vcc, s[0:1]
	v_or_b32_e32 v13, 1, v10
	v_cndmask_b32_e32 v12, 31, v12, vcc
	v_cmp_ge_u32_e32 vcc, v13, v9
	v_cmp_lt_u32_e64 s[0:1], v13, v11
	v_sub_u32_e32 v13, v13, v8
	v_max_i32_e32 v13, -15, v13
	v_add_u32_e32 v13, 15, v13
	v_min_u32_e32 v13, 30, v13
	s_and_b64 vcc, vcc, s[0:1]
	v_or_b32_e32 v14, 2, v10
	v_cndmask_b32_e32 v13, 31, v13, vcc
	v_cmp_ge_u32_e32 vcc, v14, v9
	v_cmp_lt_u32_e64 s[0:1], v14, v11
	v_sub_u32_e32 v14, v14, v8
	v_max_i32_e32 v14, -15, v14
	v_add_u32_e32 v14, 15, v14
	v_min_u32_e32 v14, 30, v14
	s_and_b64 vcc, vcc, s[0:1]
	v_or_b32_e32 v15, 3, v10
	v_cndmask_b32_e32 v14, 31, v14, vcc
	v_cmp_ge_u32_e32 vcc, v15, v9
	v_cmp_lt_u32_e64 s[0:1], v15, v11
	v_sub_u32_e32 v15, v15, v8
	v_max_i32_e32 v15, -15, v15
	v_add_u32_e32 v15, 15, v15
	v_min_u32_e32 v15, 30, v15
	s_and_b64 vcc, vcc, s[0:1]
	v_or_b32_e32 v16, 4, v10
	v_cndmask_b32_e32 v15, 31, v15, vcc
	v_cmp_ge_u32_e32 vcc, v16, v9
	v_cmp_lt_u32_e64 s[0:1], v16, v11
	v_sub_u32_e32 v16, v16, v8
	v_max_i32_e32 v16, -15, v16
	v_add_u32_e32 v16, 15, v16
	v_min_u32_e32 v16, 30, v16
	s_and_b64 vcc, vcc, s[0:1]
	v_or_b32_e32 v17, 5, v10
	v_cndmask_b32_e32 v16, 31, v16, vcc
	v_cmp_ge_u32_e32 vcc, v17, v9
	v_cmp_lt_u32_e64 s[0:1], v17, v11
	v_sub_u32_e32 v17, v17, v8
	v_max_i32_e32 v17, -15, v17
	v_add_u32_e32 v17, 15, v17
	v_min_u32_e32 v17, 30, v17
	s_and_b64 vcc, vcc, s[0:1]
	v_or_b32_e32 v18, 6, v10
	v_cndmask_b32_e32 v17, 31, v17, vcc
	v_cmp_ge_u32_e32 vcc, v18, v9
	v_cmp_lt_u32_e64 s[0:1], v18, v11
	v_sub_u32_e32 v18, v18, v8
	v_max_i32_e32 v18, -15, v18
	v_add_u32_e32 v18, 15, v18
	v_min_u32_e32 v18, 30, v18
	s_and_b64 vcc, vcc, s[0:1]
	v_or_b32_e32 v10, 7, v10
	v_cndmask_b32_e32 v18, 31, v18, vcc
	v_cmp_ge_u32_e32 vcc, v10, v9
	v_cmp_lt_u32_e64 s[0:1], v10, v11
	s_and_b64 vcc, vcc, s[0:1]
	s_add_i32 s0, s28, 0x200
	s_ashr_i32 s1, s0, 31
	s_add_u32 s0, s26, s0
	s_addc_u32 s1, s27, s1
	s_lshl_b64 s[0:1], s[0:1], 7
	s_add_u32 s0, s10, s0
	s_addc_u32 s1, s11, s1
	v_lshl_add_u64 v[252:253], s[0:1], 0, v[2:3]
	s_add_i32 s0, s28, 0x240
	s_ashr_i32 s1, s0, 31
	s_add_u32 s0, s26, s0
	s_addc_u32 s1, s27, s1
	s_lshl_b64 s[0:1], s[0:1], 7
	s_add_u32 s0, s10, s0
	s_addc_u32 s1, s11, s1
	v_lshl_add_u64 v[210:211], s[0:1], 0, v[2:3]
	s_add_i32 s0, s28, 0x280
	s_ashr_i32 s1, s0, 31
	s_add_u32 s0, s26, s0
	s_addc_u32 s1, s27, s1
	s_lshl_b64 s[0:1], s[0:1], 7
	s_add_u32 s0, s10, s0
	s_addc_u32 s1, s11, s1
	s_addk_i32 s28, 0x2c0
	v_lshl_add_u64 v[214:215], s[0:1], 0, v[2:3]
	s_ashr_i32 s1, s28, 31
	v_lshrrev_b32_e32 v6, 2, v231
	s_add_u32 s0, s26, s28
	v_lshl_add_u32 v7, v6, 3, v4
	v_sub_u32_e32 v8, v10, v8
	v_and_b32_e32 v9, 3, v5
	s_addc_u32 s1, s27, s1
	v_max_i32_e32 v8, -15, v8
	v_or_b32_e32 v7, v7, v9
	v_lshlrev_b32_e32 v234, 11, v6
	v_lshrrev_b32_e32 v6, 2, v5
	v_lshlrev_b32_e32 v5, 1, v5
	s_lshl_b64 s[0:1], s[0:1], 7
	v_add_u32_e32 v8, 15, v8
	v_lshrrev_b32_e32 v10, 1, v7
	v_lshlrev_b32_e32 v11, 1, v251
	v_and_b32_e32 v6, 2, v6
	v_and_b32_e32 v5, 4, v5
	s_add_u32 s0, s10, s0
	s_mov_b32 s23, 0
	v_min_u32_e32 v8, 30, v8
	v_bitop3_b32 v19, v10, v11, 5 bitop3:0x6c
	v_or_b32_e32 v11, 1, v11
	v_lshrrev_b32_e32 v4, 3, v4
	v_add3_u32 v5, v6, v251, v5
	s_addc_u32 s1, s11, s1
	s_mov_b32 s5, s23
	v_cndmask_b32_e32 v8, 31, v8, vcc
	v_bitop3_b32 v10, v10, v11, 5 bitop3:0x6c
	v_add_lshl_u32 v4, v5, v4, 4
	v_lshl_add_u64 v[218:219], s[0:1], 0, v[2:3]
	v_lshlrev_b32_e32 v235, 4, v19
	v_lshlrev_b32_e32 v236, 7, v9
	v_lshlrev_b32_e32 v237, 7, v7
	v_lshlrev_b32_e32 v238, 4, v10
	v_and_b32_e32 v239, 0x70, v4
	v_lshl_add_u64 v[232:233], v[252:253], 0, 16
	v_lshl_add_u64 v[212:213], v[210:211], 0, 16
	v_lshl_add_u64 v[216:217], v[214:215], 0, 16
	v_lshl_add_u64 v[220:221], v[218:219], 0, 16
	v_lshl_add_u64 v[222:223], v[202:203], 0, s[22:23]
	v_lshl_add_u64 v[224:225], v[204:205], 0, s[22:23]
	v_lshl_add_u64 v[226:227], v[202:203], 0, s[4:5]
	v_lshl_add_u64 v[228:229], v[204:205], 0, s[4:5]
	s_mov_b64 s[10:11], -1
	s_add_i32 s34, s13, 0x400
	s_add_i32 s35, s13, 0x800
	s_add_i32 s36, s13, 0xc00
	s_add_i32 s37, s13, 0x1000
	s_add_i32 s38, s13, 0x1400
	s_add_i32 s39, s13, 0x1800
	s_add_i32 s40, s13, 0x1c00
	s_add_i32 s46, 0, 0x20000
	s_mov_b32 s4, 0x3f803f80
	v_mov_b32_e32 v2, 0
	v_lshlrev_b32_e32 v240, 2, v12
	v_lshlrev_b32_e32 v241, 2, v16
	v_lshlrev_b32_e32 v242, 2, v13
	v_lshlrev_b32_e32 v243, 2, v17
	v_lshlrev_b32_e32 v244, 2, v14
	v_lshlrev_b32_e32 v245, 2, v18
	v_lshlrev_b32_e32 v246, 2, v15
	v_lshlrev_b32_e32 v247, 2, v8
	v_mbcnt_hi_u32_b32 v230, -1, v1
	v_mov_b32_e32 v6, 0x3f803f80
	s_mov_b32 s43, 0
	s_mov_b32 s5, 0
	v_readfirstlane_b32 s51, v0
	v_readlane_b32 s10, v255, 8
	v_readlane_b32 s11, v255, 9
	s_lshr_b32 s51, s51, 6
	s_and_b32 s53, s51, 3
	s_lshr_b32 s54, s51, 2
	s_lshl_b32 s55, s53, 4
	s_sub_i32 s55, s55, 8
	s_max_i32 s55, s55, 0
	s_min_i32 s55, s55, 32
	s_bfe_u32 s0, s52, 0x40003
	s_lshr_b32 s1, s52, 7
	s_add_i32 s5, s0, 16
	s_lshl_b32 s5, s5, 14
	s_lshl_b32 s6, s1, 13
	s_add_i32 s6, s5, s6
	s_mov_b32 s7, 0
	s_lshl_b64 s[6:7], s[6:7], 7
	s_add_u32 s26, s10, s6
	s_addc_u32 s27, s11, s7
	s_add_u32 s26, s26, 0x4400000
	s_addc_u32 s27, s27, 0
	s_lshl_b32 s5, s0, 14
	s_lshl_b32 s6, s1, 13
	s_add_i32 s6, s5, s6
	s_mov_b32 s7, 0
	s_lshl_b64 s[6:7], s[6:7], 7
	s_add_u32 s30, s10, s6
	s_addc_u32 s31, s11, s7
	s_add_u32 s30, s30, 0x4400000
	s_addc_u32 s31, s31, 0
	s_lshl_b32 s5, s0, 8
	s_lshl_b32 s6, s1, 7
	s_add_i32 s6, s5, s6
	s_mov_b32 s7, 0
	s_lshl_b64 s[6:7], s[6:7], 13
	s_add_u32 s28, s10, s6
	s_addc_u32 s29, s11, s7
	s_add_u32 s28, s28, 0xa400000
	s_addc_u32 s29, s29, 0
	s_lshl_b32 s5, s0, 7
	s_lshl_b32 s6, s53, 15
	s_add_i32 s5, s5, s6
	s_lshl_b32 s6, s1, 24
	s_add_i32 s5, s5, s6
	s_add_u32 s56, s10, s5
	s_addc_u32 s57, s11, 0
	s_add_u32 s56, s56, 0x8400000
	s_addc_u32 s57, s57, 0
	s_add_u32 s58, s10, s5
	s_addc_u32 s59, s11, 0
	s_add_u32 s58, s58, 0xc400000
	s_addc_u32 s59, s59, 0
	s_mul_i32 s64, s51, 0x2400
	s_add_i32 s64, s64, 0x10000
	s_cmp_eq_u32 s51, 7
	s_cselect_b32 s64, 0x21000, s64
	s_xor_b32 s0, s51, 4
	s_mul_i32 s32, s0, 0x2400
	s_add_i32 s32, s32, 0x10000
	s_cmp_eq_u32 s0, 7
	s_cselect_b32 s32, 0x21000, s32
	v_and_b32_e32 v1, 63, v0
	v_and_b32_e32 v3, 15, v1
	v_lshrrev_b32_e32 v4, 4, v1
	v_lshlrev_b32_e32 v197, 4, v1
	v_lshrrev_b32_e32 v5, 2, v3
	v_and_b32_e32 v7, 3, v3
	v_lshl_add_u32 v198, v5, 3, v7
	v_add_u32_e32 v198, s55, v198
	v_bfe_u32 v199, v198, 1, 1
	v_bfe_u32 v200, v198, 3, 1
	v_lshl_or_b32 v199, v200, 2, v199
	v_lshlrev_b32_e32 v200, 1, v4
	v_xor_b32_e32 v201, v200, v199
	v_lshlrev_b32_e32 v201, 4, v201
	v_lshl_add_u32 v188, v198, 7, v201
	v_or_b32_e32 v200, 1, v200
	v_xor_b32_e32 v201, v200, v199
	v_lshlrev_b32_e32 v201, 4, v201
	v_lshl_add_u32 v189, v198, 7, v201
	v_lshl_add_u32 v198, v5, 4, v7
	v_bfe_u32 v199, v198, 5, 1
	v_bfe_u32 v200, v198, 1, 1
	v_lshlrev_b32_e32 v199, 1, v199
	v_lshl_add_u32 v199, v200, 2, v199
	v_add_u32_e32 v199, v199, v4
	s_lshr_b32 s0, s55, 3
	v_add_u32_e32 v199, s0, v199
	v_and_b32_e32 v199, 7, v199
	v_lshlrev_b32_e32 v199, 4, v199
	v_lshl_add_u32 v190, v198, 7, v199
	v_add_u32_e32 v190, 0x2000, v190
	v_lshrrev_b32_e32 v198, 3, v1
	s_lshl_b32 s0, s51, 3
	v_add_u32_e32 v198, s0, v198
	v_and_b32_e32 v199, 7, v1
	v_bfe_u32 v200, v198, 1, 1
	v_bfe_u32 v201, v198, 3, 1
	v_lshl_or_b32 v201, v201, 2, v200
	v_xor_b32_e32 v201, v199, v201
	v_lshlrev_b32_e32 v201, 4, v201
	v_lshl_add_u32 v191, v198, 7, v201
	v_bfe_u32 v201, v198, 5, 1
	v_lshlrev_b32_e32 v201, 1, v201
	v_lshl_add_u32 v201, v200, 2, v201
	v_sub_u32_e32 v201, v199, v201
	v_and_b32_e32 v201, 7, v201
	v_lshlrev_b32_e32 v201, 4, v201
	v_lshl_add_u32 v192, v198, 7, v201
	v_lshlrev_b32_e32 v198, 5, v4
	v_lshl_add_u32 v193, v3, 7, v198
	v_lshl_add_u32 v196, v3, 11, v198
	v_xor_b32_e32 v198, 16, v1
	v_lshlrev_b32_e32 v194, 2, v198
	v_xor_b32_e32 v198, 32, v1
	v_lshlrev_b32_e32 v195, 2, v198
	s_lshl_b32 s0, s53, 4
	v_add_u32_e32 v5, s0, v3
	v_sub_u32_e64 v7, v5, 8 clamp
	v_min_u32_e32 v7, 48, v7
	v_add_u32_e32 v198, 16, v7
	v_lshlrev_b32_e32 v199, 3, v4
	v_add_u32_e32 v199, s55, v199
	v_add_u32_e32 v200, 0, v199
	v_sub_u32_e32 v201, v200, v5
	v_add_u32_e32 v201, 15, v201
	v_max_i32_e32 v201, 0, v201
	v_min_i32_e32 v201, 30, v201
	v_cmp_ge_u32_e32 vcc, v200, v7
	v_cmp_lt_u32_e64 s[0:1], v200, v198
	s_and_b64 vcc, vcc, s[0:1]
	v_mov_b32_e32 v206, 31
	v_cndmask_b32_e32 v201, v206, v201, vcc
	v_lshlrev_b32_e32 v201, 2, v201
	v_add_u32_e32 v180, 0x20000, v201
	v_add_u32_e32 v200, 1, v199
	v_sub_u32_e32 v201, v200, v5
	v_add_u32_e32 v201, 15, v201
	v_max_i32_e32 v201, 0, v201
	v_min_i32_e32 v201, 30, v201
	v_cmp_ge_u32_e32 vcc, v200, v7
	v_cmp_lt_u32_e64 s[0:1], v200, v198
	s_and_b64 vcc, vcc, s[0:1]
	v_mov_b32_e32 v206, 31
	v_cndmask_b32_e32 v201, v206, v201, vcc
	v_lshlrev_b32_e32 v201, 2, v201
	v_add_u32_e32 v181, 0x20000, v201
	v_add_u32_e32 v200, 2, v199
	v_sub_u32_e32 v201, v200, v5
	v_add_u32_e32 v201, 15, v201
	v_max_i32_e32 v201, 0, v201
	v_min_i32_e32 v201, 30, v201
	v_cmp_ge_u32_e32 vcc, v200, v7
	v_cmp_lt_u32_e64 s[0:1], v200, v198
	s_and_b64 vcc, vcc, s[0:1]
	v_mov_b32_e32 v206, 31
	v_cndmask_b32_e32 v201, v206, v201, vcc
	v_lshlrev_b32_e32 v201, 2, v201
	v_add_u32_e32 v182, 0x20000, v201
	v_add_u32_e32 v200, 3, v199
	v_sub_u32_e32 v201, v200, v5
	v_add_u32_e32 v201, 15, v201
	v_max_i32_e32 v201, 0, v201
	v_min_i32_e32 v201, 30, v201
	v_cmp_ge_u32_e32 vcc, v200, v7
	v_cmp_lt_u32_e64 s[0:1], v200, v198
	s_and_b64 vcc, vcc, s[0:1]
	v_mov_b32_e32 v206, 31
	v_cndmask_b32_e32 v201, v206, v201, vcc
	v_lshlrev_b32_e32 v201, 2, v201
	v_add_u32_e32 v183, 0x20000, v201
	v_add_u32_e32 v200, 4, v199
	v_sub_u32_e32 v201, v200, v5
	v_add_u32_e32 v201, 15, v201
	v_max_i32_e32 v201, 0, v201
	v_min_i32_e32 v201, 30, v201
	v_cmp_ge_u32_e32 vcc, v200, v7
	v_cmp_lt_u32_e64 s[0:1], v200, v198
	s_and_b64 vcc, vcc, s[0:1]
	v_mov_b32_e32 v206, 31
	v_cndmask_b32_e32 v201, v206, v201, vcc
	v_lshlrev_b32_e32 v201, 2, v201
	v_add_u32_e32 v184, 0x20000, v201
	v_add_u32_e32 v200, 5, v199
	v_sub_u32_e32 v201, v200, v5
	v_add_u32_e32 v201, 15, v201
	v_max_i32_e32 v201, 0, v201
	v_min_i32_e32 v201, 30, v201
	v_cmp_ge_u32_e32 vcc, v200, v7
	v_cmp_lt_u32_e64 s[0:1], v200, v198
	s_and_b64 vcc, vcc, s[0:1]
	v_mov_b32_e32 v206, 31
	v_cndmask_b32_e32 v201, v206, v201, vcc
	v_lshlrev_b32_e32 v201, 2, v201
	v_add_u32_e32 v185, 0x20000, v201
	v_add_u32_e32 v200, 6, v199
	v_sub_u32_e32 v201, v200, v5
	v_add_u32_e32 v201, 15, v201
	v_max_i32_e32 v201, 0, v201
	v_min_i32_e32 v201, 30, v201
	v_cmp_ge_u32_e32 vcc, v200, v7
	v_cmp_lt_u32_e64 s[0:1], v200, v198
	s_and_b64 vcc, vcc, s[0:1]
	v_mov_b32_e32 v206, 31
	v_cndmask_b32_e32 v201, v206, v201, vcc
	v_lshlrev_b32_e32 v201, 2, v201
	v_add_u32_e32 v186, 0x20000, v201
	v_add_u32_e32 v200, 7, v199
	v_sub_u32_e32 v201, v200, v5
	v_add_u32_e32 v201, 15, v201
	v_max_i32_e32 v201, 0, v201
	v_min_i32_e32 v201, 30, v201
	v_cmp_ge_u32_e32 vcc, v200, v7
	v_cmp_lt_u32_e64 s[0:1], v200, v198
	s_and_b64 vcc, vcc, s[0:1]
	v_mov_b32_e32 v206, 31
	v_cndmask_b32_e32 v201, v206, v201, vcc
	v_lshlrev_b32_e32 v201, 2, v201
	v_add_u32_e32 v187, 0x20000, v201
	v_mov_b32_e32 v176, 0x3f803f80
	v_mov_b32_e32 v177, 0x3f803f80
	v_mov_b32_e32 v178, 0x3f803f80
	v_mov_b32_e32 v179, 0x3f803f80
	s_mov_b32 s62, 0
	s_mov_b32 s63, 0
	s_lshl_b32 s41, s52, 4
	s_and_b32 s41, s41, 0x70
	s_add_i32 s42, s41, -4
	s_max_i32 s42, s42, 0
	s_min_i32 s42, s42, 0x78
	s_add_i32 s43, s41, 3
	s_max_i32 s43, s43, 0
	s_min_i32 s43, s43, 0x78
	s_add_i32 s43, s43, 7
	s_sub_i32 s45, s43, s42
	s_add_i32 s45, s45, 2
	s_lshr_b32 s45, s45, 1
	s_add_i32 s47, s41, s54
	s_add_i32 s47, s47, -4
	s_max_i32 s47, s47, 0
	s_min_i32 s47, s47, 0x78
	s_add_i32 s48, s41, s54
	s_add_i32 s48, s48, -2
	s_max_i32 s48, s48, 0
	s_min_i32 s48, s48, 0x78
	s_add_i32 s49, s41, s54
	s_add_i32 s49, s49, 0
	s_max_i32 s49, s49, 0
	s_min_i32 s49, s49, 0x78
	s_add_i32 s50, s41, s54
	s_add_i32 s50, s50, 2
	s_max_i32 s50, s50, 0
	s_min_i32 s50, s50, 0x78
	s_add_i32 s5, s41, s54
	s_add_i32 s5, s5, 0
	s_lshl_b32 s5, s5, 6
	s_lshl_b32 s6, s53, 4
	s_add_i32 s5, s5, s6
	s_lshl_b32 s5, s5, 7
	s_add_u32 s0, s30, s5
	s_addc_u32 s1, s31, 0
	global_load_dwordx4 v[92:95], v193, s[0:1]
	global_load_dwordx4 v[96:99], v193, s[0:1] offset:16
	s_add_i32 s5, s41, s54
	s_add_i32 s5, s5, 2
	s_lshl_b32 s5, s5, 6
	s_lshl_b32 s6, s53, 4
	s_add_i32 s5, s5, s6
	s_lshl_b32 s5, s5, 7
	s_add_u32 s0, s30, s5
	s_addc_u32 s1, s31, 0
	global_load_dwordx4 v[100:103], v193, s[0:1]
	global_load_dwordx4 v[104:107], v193, s[0:1] offset:16
	s_add_i32 s5, s41, s54
	s_add_i32 s5, s5, 4
	s_lshl_b32 s5, s5, 6
	s_lshl_b32 s6, s53, 4
	s_add_i32 s5, s5, s6
	s_lshl_b32 s5, s5, 7
	s_add_u32 s0, s30, s5
	s_addc_u32 s1, s31, 0
	global_load_dwordx4 v[108:111], v193, s[0:1]
	global_load_dwordx4 v[112:115], v193, s[0:1] offset:16
	s_add_i32 s5, s41, s54
	s_add_i32 s5, s5, 6
	s_lshl_b32 s5, s5, 6
	s_lshl_b32 s6, s53, 4
	s_add_i32 s5, s5, s6
	s_lshl_b32 s5, s5, 7
	s_add_u32 s0, s30, s5
	s_addc_u32 s1, s31, 0
	global_load_dwordx4 v[116:119], v193, s[0:1]
	global_load_dwordx4 v[120:123], v193, s[0:1] offset:16
	s_and_b32 s5, s62, 1
	s_lshl_b32 s5, s5, 15
	s_lshl_b32 s6, s51, 10
	s_add_i32 s5, s5, s6
	s_add_i32 s6, s42, 0
	s_min_i32 s6, s6, s43
	s_lshl_b32 s6, s6, 13
	s_add_u32 s0, s26, s6
	s_addc_u32 s1, s27, 0
	s_add_i32 m0, s5, 0x0
	s_nop 0
	global_load_lds_dwordx4 v191, s[0:1]
	s_add_u32 s0, s28, s6
	s_addc_u32 s1, s29, 0
	s_add_i32 m0, s5, 0x2000
	s_nop 0
	global_load_lds_dwordx4 v192, s[0:1]
	s_add_i32 s6, s42, 1
	s_min_i32 s6, s6, s43
	s_lshl_b32 s6, s6, 13
	s_add_u32 s0, s26, s6
	s_addc_u32 s1, s27, 0
	s_add_i32 m0, s5, 0x4000
	s_nop 0
	global_load_lds_dwordx4 v191, s[0:1]
	s_add_u32 s0, s28, s6
	s_addc_u32 s1, s29, 0
	s_add_i32 m0, s5, 0x6000
	s_nop 0
	global_load_lds_dwordx4 v192, s[0:1]
.La0_round:
	v_mov_b32_e32 v88, 0xf149f2ca
	v_mov_b32_e32 v72, 0
	v_mov_b32_e32 v73, 0
	v_mov_b32_e32 v74, 0
	v_mov_b32_e32 v75, 0
	v_mov_b32_e32 v8, 0
	v_mov_b32_e32 v9, 0
	v_mov_b32_e32 v10, 0
	v_mov_b32_e32 v11, 0
	v_mov_b32_e32 v12, 0
	v_mov_b32_e32 v13, 0
	v_mov_b32_e32 v14, 0
	v_mov_b32_e32 v15, 0
	v_mov_b32_e32 v16, 0
	v_mov_b32_e32 v17, 0
	v_mov_b32_e32 v18, 0
	v_mov_b32_e32 v19, 0
	v_mov_b32_e32 v20, 0
	v_mov_b32_e32 v21, 0
	v_mov_b32_e32 v22, 0
	v_mov_b32_e32 v23, 0
	v_mov_b32_e32 v89, 0xf149f2ca
	v_mov_b32_e32 v76, 0
	v_mov_b32_e32 v77, 0
	v_mov_b32_e32 v78, 0
	v_mov_b32_e32 v79, 0
	v_mov_b32_e32 v24, 0
	v_mov_b32_e32 v25, 0
	v_mov_b32_e32 v26, 0
	v_mov_b32_e32 v27, 0
	v_mov_b32_e32 v28, 0
	v_mov_b32_e32 v29, 0
	v_mov_b32_e32 v30, 0
	v_mov_b32_e32 v31, 0
	v_mov_b32_e32 v32, 0
	v_mov_b32_e32 v33, 0
	v_mov_b32_e32 v34, 0
	v_mov_b32_e32 v35, 0
	v_mov_b32_e32 v36, 0
	v_mov_b32_e32 v37, 0
	v_mov_b32_e32 v38, 0
	v_mov_b32_e32 v39, 0
	v_mov_b32_e32 v90, 0xf149f2ca
	v_mov_b32_e32 v80, 0
	v_mov_b32_e32 v81, 0
	v_mov_b32_e32 v82, 0
	v_mov_b32_e32 v83, 0
	v_mov_b32_e32 v40, 0
	v_mov_b32_e32 v41, 0
	v_mov_b32_e32 v42, 0
	v_mov_b32_e32 v43, 0
	v_mov_b32_e32 v44, 0
	v_mov_b32_e32 v45, 0
	v_mov_b32_e32 v46, 0
	v_mov_b32_e32 v47, 0
	v_mov_b32_e32 v48, 0
	v_mov_b32_e32 v49, 0
	v_mov_b32_e32 v50, 0
	v_mov_b32_e32 v51, 0
	v_mov_b32_e32 v52, 0
	v_mov_b32_e32 v53, 0
	v_mov_b32_e32 v54, 0
	v_mov_b32_e32 v55, 0
	v_mov_b32_e32 v91, 0xf149f2ca
	v_mov_b32_e32 v84, 0
	v_mov_b32_e32 v85, 0
	v_mov_b32_e32 v86, 0
	v_mov_b32_e32 v87, 0
	v_mov_b32_e32 v56, 0
	v_mov_b32_e32 v57, 0
	v_mov_b32_e32 v58, 0
	v_mov_b32_e32 v59, 0
	v_mov_b32_e32 v60, 0
	v_mov_b32_e32 v61, 0
	v_mov_b32_e32 v62, 0
	v_mov_b32_e32 v63, 0
	v_mov_b32_e32 v64, 0
	v_mov_b32_e32 v65, 0
	v_mov_b32_e32 v66, 0
	v_mov_b32_e32 v67, 0
	v_mov_b32_e32 v68, 0
	v_mov_b32_e32 v69, 0
	v_mov_b32_e32 v70, 0
	v_mov_b32_e32 v71, 0
	s_mov_b32 s44, 0
.La0_ss:
	s_waitcnt vmcnt(0) lgkmcnt(0)
	s_barrier
	s_lshl_b32 s60, s44, 1
	s_add_i32 s60, s60, s42
	s_cmp_gt_i32 s60, s43
	s_cbranch_scc1 .La0_noread
	s_cmp_lt_i32 s60, s47
	s_cbranch_scc1 .La0_noread
	s_add_i32 s0, s50, 7
	s_cmp_gt_i32 s60, s0
	s_cbranch_scc1 .La0_noread
	s_and_b32 s61, s62, 1
	s_lshl_b32 s61, s61, 15
	v_add_u32_e32 v207, s61, v188
	v_add_u32_e32 v208, s61, v189
	v_add_u32_e32 v209, s61, v190
	ds_read_b128 v[124:127], v207
	ds_read_b128 v[132:135], v207 offset:512
	ds_read_b128 v[128:131], v208
	ds_read_b128 v[136:139], v208 offset:512
	ds_read_b128 v[140:143], v209 offset:0
	ds_read_b128 v[144:147], v209 offset:512
	ds_read_b128 v[148:151], v209 offset:1024
	ds_read_b128 v[152:155], v209 offset:1536
	s_sub_i32 s0, s60, s41
	s_sub_i32 s0, s0, s54
	s_add_i32 s0, s0, 1
	s_lshl_b32 s0, s0, 7
	v_add_u32_e32 v167, s0, v180
	v_add_u32_e32 v168, s0, v181
	v_add_u32_e32 v169, s0, v182
	v_add_u32_e32 v170, s0, v183
	v_add_u32_e32 v171, s0, v184
	v_add_u32_e32 v243, s0, v185
	v_add_u32_e32 v244, s0, v186
	v_add_u32_e32 v245, s0, v187
.La0_noread:
	s_add_i32 s7, s44, 1
	s_cmp_lt_u32 s7, s45
	s_cbranch_scc0 .La0_issue_next_round
	s_lshl_b32 s7, s7, 1
	s_add_i32 s7, s7, s42
	s_add_i32 s22, s62, 1
	s_mov_b32 s98, s7
	s_and_b32 s5, s22, 1
	s_lshl_b32 s5, s5, 15
	s_lshl_b32 s6, s51, 10
	s_add_i32 s5, s5, s6
	s_add_i32 s6, s98, 0
	s_min_i32 s6, s6, s43
	s_lshl_b32 s6, s6, 13
	s_add_u32 s0, s26, s6
	s_addc_u32 s1, s27, 0
	s_add_i32 m0, s5, 0x0
	s_nop 0
	global_load_lds_dwordx4 v191, s[0:1]
	s_add_u32 s0, s28, s6
	s_addc_u32 s1, s29, 0
	s_add_i32 m0, s5, 0x2000
	s_nop 0
	global_load_lds_dwordx4 v192, s[0:1]
	s_add_i32 s6, s98, 1
	s_min_i32 s6, s6, s43
	s_lshl_b32 s6, s6, 13
	s_add_u32 s0, s26, s6
	s_addc_u32 s1, s27, 0
	s_add_i32 m0, s5, 0x4000
	s_nop 0
	global_load_lds_dwordx4 v191, s[0:1]
	s_add_u32 s0, s28, s6
	s_addc_u32 s1, s29, 0
	s_add_i32 m0, s5, 0x6000
	s_nop 0
	global_load_lds_dwordx4 v192, s[0:1]
	s_branch .La0_issued
.La0_issue_next_round:
	s_cmp_lt_u32 s63, 1
	s_cbranch_scc0 .La0_gateld
	s_add_i32 s98, s41, 8
	s_add_i32 s99, s98, -4
	s_max_i32 s99, s99, 0
	s_min_i32 s99, s99, 0x78
	s_add_i32 s100, s98, 3
	s_max_i32 s100, s100, 0
	s_min_i32 s100, s100, 0x78
	s_add_i32 s100, s100, 7
	s_sub_i32 s101, s100, s99
	s_add_i32 s101, s101, 2
	s_lshr_b32 s101, s101, 1
	s_add_i32 s22, s62, 1
	s_and_b32 s5, s22, 1
	s_lshl_b32 s5, s5, 15
	s_lshl_b32 s6, s51, 10
	s_add_i32 s5, s5, s6
	s_add_i32 s6, s99, 0
	s_min_i32 s6, s6, s100
	s_lshl_b32 s6, s6, 13
	s_add_u32 s0, s26, s6
	s_addc_u32 s1, s27, 0
	s_add_i32 m0, s5, 0x0
	s_nop 0
	global_load_lds_dwordx4 v191, s[0:1]
	s_add_u32 s0, s28, s6
	s_addc_u32 s1, s29, 0
	s_add_i32 m0, s5, 0x2000
	s_nop 0
	global_load_lds_dwordx4 v192, s[0:1]
	s_add_i32 s6, s99, 1
	s_min_i32 s6, s6, s100
	s_lshl_b32 s6, s6, 13
	s_add_u32 s0, s26, s6
	s_addc_u32 s1, s27, 0
	s_add_i32 m0, s5, 0x4000
	s_nop 0
	global_load_lds_dwordx4 v191, s[0:1]
	s_add_u32 s0, s28, s6
	s_addc_u32 s1, s29, 0
	s_add_i32 m0, s5, 0x6000
	s_nop 0
	global_load_lds_dwordx4 v192, s[0:1]
.La0_gateld:
	s_add_i32 s5, s41, s54
	s_add_i32 s5, s5, 0
	s_lshl_b32 s5, s5, 17
	s_add_u32 s0, s56, s5
	s_addc_u32 s1, s57, 0
	global_load_dwordx4 v[210:213], v196, s[0:1] nt
	global_load_dwordx4 v[214:217], v196, s[0:1] offset:16 nt
	s_add_i32 s5, s41, s54
	s_add_i32 s5, s5, 2
	s_lshl_b32 s5, s5, 17
	s_add_u32 s0, s56, s5
	s_addc_u32 s1, s57, 0
	global_load_dwordx4 v[218:221], v196, s[0:1] nt
	global_load_dwordx4 v[222:225], v196, s[0:1] offset:16 nt
.La0_issued:
	s_lshl_b32 s60, s44, 1
	s_add_i32 s60, s60, s42
	s_cmp_gt_i32 s60, s43
	s_cbranch_scc1 .La0_k0done
	s_cmp_lt_i32 s60, s47
	s_cbranch_scc1 .La0_k0done
	s_add_i32 s0, s50, 7
	s_cmp_gt_i32 s60, s0
	s_cbranch_scc1 .La0_k0done
	s_sub_i32 s0, s60, s47
	s_cmp_le_u32 s0, 7
	s_cselect_b32 s6, 1, 0
	s_sub_i32 s0, s60, s48
	s_cmp_le_u32 s0, 7
	s_cselect_b32 s7, 1, 0
	s_and_b32 s0, s6, s7
	s_cmp_lg_u32 s0, 0
	s_cbranch_scc0 .La0_notboth_a0
	ds_read_b32 v156, v167 offset:768
	ds_read_b32 v157, v168 offset:768
	ds_read_b32 v158, v169 offset:768
	ds_read_b32 v159, v170 offset:768
	ds_read_b32 v160, v171 offset:768
	ds_read_b32 v161, v243 offset:768
	ds_read_b32 v162, v244 offset:768
	ds_read_b32 v163, v245 offset:768
	ds_read_b32 v232, v167 offset:512
	ds_read_b32 v233, v168 offset:512
	ds_read_b32 v234, v169 offset:512
	ds_read_b32 v235, v170 offset:512
	ds_read_b32 v236, v171 offset:512
	ds_read_b32 v237, v243 offset:512
	ds_read_b32 v238, v244 offset:512
	ds_read_b32 v239, v245 offset:512
	s_waitcnt lgkmcnt(8)
	v_mfma_f32_16x16x32_bf16 v[156:159], v[124:127], v[92:95], v[156:159]
	v_mfma_f32_16x16x32_bf16 v[160:163], v[132:135], v[92:95], v[160:163]
	s_waitcnt lgkmcnt(0)
	v_mfma_f32_16x16x32_bf16 v[232:235], v[124:127], v[100:103], v[232:235]
	v_mfma_f32_16x16x32_bf16 v[236:239], v[132:135], v[100:103], v[236:239]
	v_mfma_f32_16x16x32_bf16 v[156:159], v[128:131], v[96:99], v[156:159]
	v_mfma_f32_16x16x32_bf16 v[160:163], v[136:139], v[96:99], v[160:163]
	v_mfma_f32_16x16x32_bf16 v[232:235], v[128:131], v[104:107], v[232:235]
	v_mfma_f32_16x16x32_bf16 v[236:239], v[136:139], v[104:107], v[236:239]
	v_add_f32_e32 v164, 0x41000000, v88
	v_add_f32_e32 v240, 0x41000000, v89
	s_nop 4
	v_max3_f32 v165, v156, v157, v158
	v_max3_f32 v166, v159, v160, v161
	v_max3_f32 v165, v165, v162, v163
	v_max_f32_e32 v165, v165, v166
	v_max3_f32 v241, v232, v233, v234
	v_max3_f32 v242, v235, v236, v237
	v_max3_f32 v241, v241, v238, v239
	v_max_f32_e32 v241, v241, v242
	v_cmp_gt_f32_e32 vcc, v165, v164
	v_cmp_gt_f32_e64 s[0:1], v241, v240
	s_or_b64 vcc, vcc, s[0:1]
	s_cbranch_vccz .La0_pnors_1
	ds_bpermute_b32 v166, v194, v165
	ds_bpermute_b32 v242, v194, v241
	s_waitcnt lgkmcnt(0)
	v_max_f32_e32 v165, v165, v166
	v_max_f32_e32 v241, v241, v242
	ds_bpermute_b32 v166, v195, v165
	ds_bpermute_b32 v242, v195, v241
	s_waitcnt lgkmcnt(0)
	v_max3_f32 v165, v165, v166, v88
	v_max3_f32 v241, v241, v242, v89
	v_sub_f32_e32 v166, v88, v165
	v_sub_f32_e32 v242, v89, v241
	v_exp_f32_e32 v166, v166
	v_exp_f32_e32 v242, v242
	v_mov_b32_e32 v88, v165
	v_mov_b32_e32 v89, v241
	v_mul_f32_e32 v72, v72, v166
	v_mul_f32_e32 v73, v73, v166
	v_mul_f32_e32 v74, v74, v166
	v_mul_f32_e32 v75, v75, v166
	v_mul_f32_e32 v8, v8, v166
	v_mul_f32_e32 v9, v9, v166
	v_mul_f32_e32 v10, v10, v166
	v_mul_f32_e32 v11, v11, v166
	v_mul_f32_e32 v12, v12, v166
	v_mul_f32_e32 v13, v13, v166
	v_mul_f32_e32 v14, v14, v166
	v_mul_f32_e32 v15, v15, v166
	v_mul_f32_e32 v16, v16, v166
	v_mul_f32_e32 v17, v17, v166
	v_mul_f32_e32 v18, v18, v166
	v_mul_f32_e32 v19, v19, v166
	v_mul_f32_e32 v20, v20, v166
	v_mul_f32_e32 v21, v21, v166
	v_mul_f32_e32 v22, v22, v166
	v_mul_f32_e32 v23, v23, v166
	v_mul_f32_e32 v76, v76, v242
	v_mul_f32_e32 v77, v77, v242
	v_mul_f32_e32 v78, v78, v242
	v_mul_f32_e32 v79, v79, v242
	v_mul_f32_e32 v24, v24, v242
	v_mul_f32_e32 v25, v25, v242
	v_mul_f32_e32 v26, v26, v242
	v_mul_f32_e32 v27, v27, v242
	v_mul_f32_e32 v28, v28, v242
	v_mul_f32_e32 v29, v29, v242
	v_mul_f32_e32 v30, v30, v242
	v_mul_f32_e32 v31, v31, v242
	v_mul_f32_e32 v32, v32, v242
	v_mul_f32_e32 v33, v33, v242
	v_mul_f32_e32 v34, v34, v242
	v_mul_f32_e32 v35, v35, v242
	v_mul_f32_e32 v36, v36, v242
	v_mul_f32_e32 v37, v37, v242
	v_mul_f32_e32 v38, v38, v242
	v_mul_f32_e32 v39, v39, v242
.La0_pnors_1:
	v_sub_f32_e32 v156, v156, v88
	v_sub_f32_e32 v157, v157, v88
	v_sub_f32_e32 v158, v158, v88
	v_sub_f32_e32 v159, v159, v88
	v_sub_f32_e32 v160, v160, v88
	v_sub_f32_e32 v161, v161, v88
	v_sub_f32_e32 v162, v162, v88
	v_sub_f32_e32 v163, v163, v88
	v_exp_f32_e32 v156, v156
	v_exp_f32_e32 v157, v157
	v_exp_f32_e32 v158, v158
	v_exp_f32_e32 v159, v159
	v_exp_f32_e32 v160, v160
	v_exp_f32_e32 v161, v161
	v_exp_f32_e32 v162, v162
	v_exp_f32_e32 v163, v163
	v_sub_f32_e32 v232, v232, v89
	v_sub_f32_e32 v233, v233, v89
	v_sub_f32_e32 v234, v234, v89
	v_sub_f32_e32 v235, v235, v89
	v_sub_f32_e32 v236, v236, v89
	v_sub_f32_e32 v237, v237, v89
	v_sub_f32_e32 v238, v238, v89
	v_sub_f32_e32 v239, v239, v89
	v_cvt_pk_bf16_f32 v172, v156, v157
	v_cvt_pk_bf16_f32 v173, v158, v159
	v_cvt_pk_bf16_f32 v174, v160, v161
	v_cvt_pk_bf16_f32 v175, v162, v163
	v_exp_f32_e32 v232, v232
	v_exp_f32_e32 v233, v233
	v_exp_f32_e32 v234, v234
	v_exp_f32_e32 v235, v235
	v_exp_f32_e32 v236, v236
	v_exp_f32_e32 v237, v237
	v_exp_f32_e32 v238, v238
	v_exp_f32_e32 v239, v239
	v_mfma_f32_16x16x32_bf16 v[8:11], v[140:143], v[172:175], v[8:11]
	v_mfma_f32_16x16x32_bf16 v[12:15], v[144:147], v[172:175], v[12:15]
	v_mfma_f32_16x16x32_bf16 v[16:19], v[148:151], v[172:175], v[16:19]
	v_mfma_f32_16x16x32_bf16 v[20:23], v[152:155], v[172:175], v[20:23]
	v_mfma_f32_16x16x32_bf16 v[72:75], v[176:179], v[172:175], v[72:75]
	v_cvt_pk_bf16_f32 v226, v232, v233
	v_cvt_pk_bf16_f32 v227, v234, v235
	v_cvt_pk_bf16_f32 v228, v236, v237
	v_cvt_pk_bf16_f32 v229, v238, v239
	s_nop 1
	v_mfma_f32_16x16x32_bf16 v[24:27], v[140:143], v[226:229], v[24:27]
	v_mfma_f32_16x16x32_bf16 v[28:31], v[144:147], v[226:229], v[28:31]
	v_mfma_f32_16x16x32_bf16 v[32:35], v[148:151], v[226:229], v[32:35]
	v_mfma_f32_16x16x32_bf16 v[36:39], v[152:155], v[226:229], v[36:39]
	v_mfma_f32_16x16x32_bf16 v[76:79], v[176:179], v[226:229], v[76:79]
	s_branch .La0_pairdone_a0
.La0_notboth_a0:
	s_cmp_lg_u32 s6, 0
	s_cbranch_scc0 .La0_notA_a0
	ds_read_b32 v156, v167 offset:768
	ds_read_b32 v157, v168 offset:768
	ds_read_b32 v158, v169 offset:768
	ds_read_b32 v159, v170 offset:768
	ds_read_b32 v160, v171 offset:768
	ds_read_b32 v161, v243 offset:768
	ds_read_b32 v162, v244 offset:768
	ds_read_b32 v163, v245 offset:768
	s_waitcnt lgkmcnt(0)
	v_mfma_f32_16x16x32_bf16 v[156:159], v[124:127], v[92:95], v[156:159]
	v_mfma_f32_16x16x32_bf16 v[160:163], v[132:135], v[92:95], v[160:163]
	v_mfma_f32_16x16x32_bf16 v[156:159], v[128:131], v[96:99], v[156:159]
	v_mfma_f32_16x16x32_bf16 v[160:163], v[136:139], v[96:99], v[160:163]
	v_add_f32_e32 v164, 0x41000000, v88
	s_nop 7
	s_nop 1
	v_max3_f32 v165, v156, v157, v158
	v_max3_f32 v166, v159, v160, v161
	v_max3_f32 v165, v165, v162, v163
	v_max_f32_e32 v165, v165, v166
	v_cmp_gt_f32_e32 vcc, v165, v164
	s_cbranch_vccz .La0_nors_2
	ds_bpermute_b32 v166, v194, v165
	s_waitcnt lgkmcnt(0)
	v_max_f32_e32 v165, v165, v166
	ds_bpermute_b32 v166, v195, v165
	s_waitcnt lgkmcnt(0)
	v_max3_f32 v165, v165, v166, v88
	v_sub_f32_e32 v166, v88, v165
	v_exp_f32_e32 v166, v166
	v_mov_b32_e32 v88, v165
	s_nop 0
	v_mul_f32_e32 v72, v72, v166
	v_mul_f32_e32 v73, v73, v166
	v_mul_f32_e32 v74, v74, v166
	v_mul_f32_e32 v75, v75, v166
	v_mul_f32_e32 v8, v8, v166
	v_mul_f32_e32 v9, v9, v166
	v_mul_f32_e32 v10, v10, v166
	v_mul_f32_e32 v11, v11, v166
	v_mul_f32_e32 v12, v12, v166
	v_mul_f32_e32 v13, v13, v166
	v_mul_f32_e32 v14, v14, v166
	v_mul_f32_e32 v15, v15, v166
	v_mul_f32_e32 v16, v16, v166
	v_mul_f32_e32 v17, v17, v166
	v_mul_f32_e32 v18, v18, v166
	v_mul_f32_e32 v19, v19, v166
	v_mul_f32_e32 v20, v20, v166
	v_mul_f32_e32 v21, v21, v166
	v_mul_f32_e32 v22, v22, v166
	v_mul_f32_e32 v23, v23, v166
.La0_nors_2:
	v_sub_f32_e32 v156, v156, v88
	v_sub_f32_e32 v157, v157, v88
	v_sub_f32_e32 v158, v158, v88
	v_sub_f32_e32 v159, v159, v88
	v_sub_f32_e32 v160, v160, v88
	v_sub_f32_e32 v161, v161, v88
	v_sub_f32_e32 v162, v162, v88
	v_sub_f32_e32 v163, v163, v88
	v_exp_f32_e32 v156, v156
	v_exp_f32_e32 v157, v157
	v_exp_f32_e32 v158, v158
	v_exp_f32_e32 v159, v159
	v_exp_f32_e32 v160, v160
	v_exp_f32_e32 v161, v161
	v_exp_f32_e32 v162, v162
	v_exp_f32_e32 v163, v163
	s_nop 0
	v_cvt_pk_bf16_f32 v172, v156, v157
	v_cvt_pk_bf16_f32 v173, v158, v159
	v_cvt_pk_bf16_f32 v174, v160, v161
	v_cvt_pk_bf16_f32 v175, v162, v163
	s_nop 1
	v_mfma_f32_16x16x32_bf16 v[8:11], v[140:143], v[172:175], v[8:11]
	v_mfma_f32_16x16x32_bf16 v[12:15], v[144:147], v[172:175], v[12:15]
	v_mfma_f32_16x16x32_bf16 v[16:19], v[148:151], v[172:175], v[16:19]
	v_mfma_f32_16x16x32_bf16 v[20:23], v[152:155], v[172:175], v[20:23]
	v_mfma_f32_16x16x32_bf16 v[72:75], v[176:179], v[172:175], v[72:75]
	s_branch .La0_pairdone_a0
.La0_notA_a0:
	s_cmp_lg_u32 s7, 0
	s_cbranch_scc0 .La0_pairdone_a0
	ds_read_b32 v156, v167 offset:512
	ds_read_b32 v157, v168 offset:512
	ds_read_b32 v158, v169 offset:512
	ds_read_b32 v159, v170 offset:512
	ds_read_b32 v160, v171 offset:512
	ds_read_b32 v161, v243 offset:512
	ds_read_b32 v162, v244 offset:512
	ds_read_b32 v163, v245 offset:512
	s_waitcnt lgkmcnt(0)
	v_mfma_f32_16x16x32_bf16 v[156:159], v[124:127], v[100:103], v[156:159]
	v_mfma_f32_16x16x32_bf16 v[160:163], v[132:135], v[100:103], v[160:163]
	v_mfma_f32_16x16x32_bf16 v[156:159], v[128:131], v[104:107], v[156:159]
	v_mfma_f32_16x16x32_bf16 v[160:163], v[136:139], v[104:107], v[160:163]
	v_add_f32_e32 v164, 0x41000000, v89
	s_nop 7
	s_nop 1
	v_max3_f32 v165, v156, v157, v158
	v_max3_f32 v166, v159, v160, v161
	v_max3_f32 v165, v165, v162, v163
	v_max_f32_e32 v165, v165, v166
	v_cmp_gt_f32_e32 vcc, v165, v164
	s_cbranch_vccz .La0_nors_3
	ds_bpermute_b32 v166, v194, v165
	s_waitcnt lgkmcnt(0)
	v_max_f32_e32 v165, v165, v166
	ds_bpermute_b32 v166, v195, v165
	s_waitcnt lgkmcnt(0)
	v_max3_f32 v165, v165, v166, v89
	v_sub_f32_e32 v166, v89, v165
	v_exp_f32_e32 v166, v166
	v_mov_b32_e32 v89, v165
	s_nop 0
	v_mul_f32_e32 v76, v76, v166
	v_mul_f32_e32 v77, v77, v166
	v_mul_f32_e32 v78, v78, v166
	v_mul_f32_e32 v79, v79, v166
	v_mul_f32_e32 v24, v24, v166
	v_mul_f32_e32 v25, v25, v166
	v_mul_f32_e32 v26, v26, v166
	v_mul_f32_e32 v27, v27, v166
	v_mul_f32_e32 v28, v28, v166
	v_mul_f32_e32 v29, v29, v166
	v_mul_f32_e32 v30, v30, v166
	v_mul_f32_e32 v31, v31, v166
	v_mul_f32_e32 v32, v32, v166
	v_mul_f32_e32 v33, v33, v166
	v_mul_f32_e32 v34, v34, v166
	v_mul_f32_e32 v35, v35, v166
	v_mul_f32_e32 v36, v36, v166
	v_mul_f32_e32 v37, v37, v166
	v_mul_f32_e32 v38, v38, v166
	v_mul_f32_e32 v39, v39, v166
.La0_nors_3:
	v_sub_f32_e32 v156, v156, v89
	v_sub_f32_e32 v157, v157, v89
	v_sub_f32_e32 v158, v158, v89
	v_sub_f32_e32 v159, v159, v89
	v_sub_f32_e32 v160, v160, v89
	v_sub_f32_e32 v161, v161, v89
	v_sub_f32_e32 v162, v162, v89
	v_sub_f32_e32 v163, v163, v89
	v_exp_f32_e32 v156, v156
	v_exp_f32_e32 v157, v157
	v_exp_f32_e32 v158, v158
	v_exp_f32_e32 v159, v159
	v_exp_f32_e32 v160, v160
	v_exp_f32_e32 v161, v161
	v_exp_f32_e32 v162, v162
	v_exp_f32_e32 v163, v163
	s_nop 0
	v_cvt_pk_bf16_f32 v172, v156, v157
	v_cvt_pk_bf16_f32 v173, v158, v159
	v_cvt_pk_bf16_f32 v174, v160, v161
	v_cvt_pk_bf16_f32 v175, v162, v163
	s_nop 1
	v_mfma_f32_16x16x32_bf16 v[24:27], v[140:143], v[172:175], v[24:27]
	v_mfma_f32_16x16x32_bf16 v[28:31], v[144:147], v[172:175], v[28:31]
	v_mfma_f32_16x16x32_bf16 v[32:35], v[148:151], v[172:175], v[32:35]
	v_mfma_f32_16x16x32_bf16 v[36:39], v[152:155], v[172:175], v[36:39]
	v_mfma_f32_16x16x32_bf16 v[76:79], v[176:179], v[172:175], v[76:79]
.La0_pairdone_a0:
	s_sub_i32 s0, s60, s49
	s_cmp_le_u32 s0, 7
	s_cselect_b32 s6, 1, 0
	s_sub_i32 s0, s60, s50
	s_cmp_le_u32 s0, 7
	s_cselect_b32 s7, 1, 0
	s_and_b32 s0, s6, s7
	s_cmp_lg_u32 s0, 0
	s_cbranch_scc0 .La0_notboth_a1
	ds_read_b32 v156, v167 offset:256
	ds_read_b32 v157, v168 offset:256
	ds_read_b32 v158, v169 offset:256
	ds_read_b32 v159, v170 offset:256
	ds_read_b32 v160, v171 offset:256
	ds_read_b32 v161, v243 offset:256
	ds_read_b32 v162, v244 offset:256
	ds_read_b32 v163, v245 offset:256
	ds_read_b32 v232, v167 offset:0
	ds_read_b32 v233, v168 offset:0
	ds_read_b32 v234, v169 offset:0
	ds_read_b32 v235, v170 offset:0
	ds_read_b32 v236, v171 offset:0
	ds_read_b32 v237, v243 offset:0
	ds_read_b32 v238, v244 offset:0
	ds_read_b32 v239, v245 offset:0
	s_waitcnt lgkmcnt(8)
	v_mfma_f32_16x16x32_bf16 v[156:159], v[124:127], v[108:111], v[156:159]
	v_mfma_f32_16x16x32_bf16 v[160:163], v[132:135], v[108:111], v[160:163]
	s_waitcnt lgkmcnt(0)
	v_mfma_f32_16x16x32_bf16 v[232:235], v[124:127], v[116:119], v[232:235]
	v_mfma_f32_16x16x32_bf16 v[236:239], v[132:135], v[116:119], v[236:239]
	v_mfma_f32_16x16x32_bf16 v[156:159], v[128:131], v[112:115], v[156:159]
	v_mfma_f32_16x16x32_bf16 v[160:163], v[136:139], v[112:115], v[160:163]
	v_mfma_f32_16x16x32_bf16 v[232:235], v[128:131], v[120:123], v[232:235]
	v_mfma_f32_16x16x32_bf16 v[236:239], v[136:139], v[120:123], v[236:239]
	v_add_f32_e32 v164, 0x41000000, v90
	v_add_f32_e32 v240, 0x41000000, v91
	s_nop 4
	v_max3_f32 v165, v156, v157, v158
	v_max3_f32 v166, v159, v160, v161
	v_max3_f32 v165, v165, v162, v163
	v_max_f32_e32 v165, v165, v166
	v_max3_f32 v241, v232, v233, v234
	v_max3_f32 v242, v235, v236, v237
	v_max3_f32 v241, v241, v238, v239
	v_max_f32_e32 v241, v241, v242
	v_cmp_gt_f32_e32 vcc, v165, v164
	v_cmp_gt_f32_e64 s[0:1], v241, v240
	s_or_b64 vcc, vcc, s[0:1]
	s_cbranch_vccz .La0_pnors_4
	ds_bpermute_b32 v166, v194, v165
	ds_bpermute_b32 v242, v194, v241
	s_waitcnt lgkmcnt(0)
	v_max_f32_e32 v165, v165, v166
	v_max_f32_e32 v241, v241, v242
	ds_bpermute_b32 v166, v195, v165
	ds_bpermute_b32 v242, v195, v241
	s_waitcnt lgkmcnt(0)
	v_max3_f32 v165, v165, v166, v90
	v_max3_f32 v241, v241, v242, v91
	v_sub_f32_e32 v166, v90, v165
	v_sub_f32_e32 v242, v91, v241
	v_exp_f32_e32 v166, v166
	v_exp_f32_e32 v242, v242
	v_mov_b32_e32 v90, v165
	v_mov_b32_e32 v91, v241
	v_mul_f32_e32 v80, v80, v166
	v_mul_f32_e32 v81, v81, v166
	v_mul_f32_e32 v82, v82, v166
	v_mul_f32_e32 v83, v83, v166
	v_mul_f32_e32 v40, v40, v166
	v_mul_f32_e32 v41, v41, v166
	v_mul_f32_e32 v42, v42, v166
	v_mul_f32_e32 v43, v43, v166
	v_mul_f32_e32 v44, v44, v166
	v_mul_f32_e32 v45, v45, v166
	v_mul_f32_e32 v46, v46, v166
	v_mul_f32_e32 v47, v47, v166
	v_mul_f32_e32 v48, v48, v166
	v_mul_f32_e32 v49, v49, v166
	v_mul_f32_e32 v50, v50, v166
	v_mul_f32_e32 v51, v51, v166
	v_mul_f32_e32 v52, v52, v166
	v_mul_f32_e32 v53, v53, v166
	v_mul_f32_e32 v54, v54, v166
	v_mul_f32_e32 v55, v55, v166
	v_mul_f32_e32 v84, v84, v242
	v_mul_f32_e32 v85, v85, v242
	v_mul_f32_e32 v86, v86, v242
	v_mul_f32_e32 v87, v87, v242
	v_mul_f32_e32 v56, v56, v242
	v_mul_f32_e32 v57, v57, v242
	v_mul_f32_e32 v58, v58, v242
	v_mul_f32_e32 v59, v59, v242
	v_mul_f32_e32 v60, v60, v242
	v_mul_f32_e32 v61, v61, v242
	v_mul_f32_e32 v62, v62, v242
	v_mul_f32_e32 v63, v63, v242
	v_mul_f32_e32 v64, v64, v242
	v_mul_f32_e32 v65, v65, v242
	v_mul_f32_e32 v66, v66, v242
	v_mul_f32_e32 v67, v67, v242
	v_mul_f32_e32 v68, v68, v242
	v_mul_f32_e32 v69, v69, v242
	v_mul_f32_e32 v70, v70, v242
	v_mul_f32_e32 v71, v71, v242
.La0_pnors_4:
	v_sub_f32_e32 v156, v156, v90
	v_sub_f32_e32 v157, v157, v90
	v_sub_f32_e32 v158, v158, v90
	v_sub_f32_e32 v159, v159, v90
	v_sub_f32_e32 v160, v160, v90
	v_sub_f32_e32 v161, v161, v90
	v_sub_f32_e32 v162, v162, v90
	v_sub_f32_e32 v163, v163, v90
	v_exp_f32_e32 v156, v156
	v_exp_f32_e32 v157, v157
	v_exp_f32_e32 v158, v158
	v_exp_f32_e32 v159, v159
	v_exp_f32_e32 v160, v160
	v_exp_f32_e32 v161, v161
	v_exp_f32_e32 v162, v162
	v_exp_f32_e32 v163, v163
	v_sub_f32_e32 v232, v232, v91
	v_sub_f32_e32 v233, v233, v91
	v_sub_f32_e32 v234, v234, v91
	v_sub_f32_e32 v235, v235, v91
	v_sub_f32_e32 v236, v236, v91
	v_sub_f32_e32 v237, v237, v91
	v_sub_f32_e32 v238, v238, v91
	v_sub_f32_e32 v239, v239, v91
	v_cvt_pk_bf16_f32 v172, v156, v157
	v_cvt_pk_bf16_f32 v173, v158, v159
	v_cvt_pk_bf16_f32 v174, v160, v161
	v_cvt_pk_bf16_f32 v175, v162, v163
	v_exp_f32_e32 v232, v232
	v_exp_f32_e32 v233, v233
	v_exp_f32_e32 v234, v234
	v_exp_f32_e32 v235, v235
	v_exp_f32_e32 v236, v236
	v_exp_f32_e32 v237, v237
	v_exp_f32_e32 v238, v238
	v_exp_f32_e32 v239, v239
	v_mfma_f32_16x16x32_bf16 v[40:43], v[140:143], v[172:175], v[40:43]
	v_mfma_f32_16x16x32_bf16 v[44:47], v[144:147], v[172:175], v[44:47]
	v_mfma_f32_16x16x32_bf16 v[48:51], v[148:151], v[172:175], v[48:51]
	v_mfma_f32_16x16x32_bf16 v[52:55], v[152:155], v[172:175], v[52:55]
	v_mfma_f32_16x16x32_bf16 v[80:83], v[176:179], v[172:175], v[80:83]
	v_cvt_pk_bf16_f32 v226, v232, v233
	v_cvt_pk_bf16_f32 v227, v234, v235
	v_cvt_pk_bf16_f32 v228, v236, v237
	v_cvt_pk_bf16_f32 v229, v238, v239
	s_nop 1
	v_mfma_f32_16x16x32_bf16 v[56:59], v[140:143], v[226:229], v[56:59]
	v_mfma_f32_16x16x32_bf16 v[60:63], v[144:147], v[226:229], v[60:63]
	v_mfma_f32_16x16x32_bf16 v[64:67], v[148:151], v[226:229], v[64:67]
	v_mfma_f32_16x16x32_bf16 v[68:71], v[152:155], v[226:229], v[68:71]
	v_mfma_f32_16x16x32_bf16 v[84:87], v[176:179], v[226:229], v[84:87]
	s_branch .La0_pairdone_a1
.La0_notboth_a1:
	s_cmp_lg_u32 s6, 0
	s_cbranch_scc0 .La0_notA_a1
	ds_read_b32 v156, v167 offset:256
	ds_read_b32 v157, v168 offset:256
	ds_read_b32 v158, v169 offset:256
	ds_read_b32 v159, v170 offset:256
	ds_read_b32 v160, v171 offset:256
	ds_read_b32 v161, v243 offset:256
	ds_read_b32 v162, v244 offset:256
	ds_read_b32 v163, v245 offset:256
	s_waitcnt lgkmcnt(0)
	v_mfma_f32_16x16x32_bf16 v[156:159], v[124:127], v[108:111], v[156:159]
	v_mfma_f32_16x16x32_bf16 v[160:163], v[132:135], v[108:111], v[160:163]
	v_mfma_f32_16x16x32_bf16 v[156:159], v[128:131], v[112:115], v[156:159]
	v_mfma_f32_16x16x32_bf16 v[160:163], v[136:139], v[112:115], v[160:163]
	v_add_f32_e32 v164, 0x41000000, v90
	s_nop 7
	s_nop 1
	v_max3_f32 v165, v156, v157, v158
	v_max3_f32 v166, v159, v160, v161
	v_max3_f32 v165, v165, v162, v163
	v_max_f32_e32 v165, v165, v166
	v_cmp_gt_f32_e32 vcc, v165, v164
	s_cbranch_vccz .La0_nors_5
	ds_bpermute_b32 v166, v194, v165
	s_waitcnt lgkmcnt(0)
	v_max_f32_e32 v165, v165, v166
	ds_bpermute_b32 v166, v195, v165
	s_waitcnt lgkmcnt(0)
	v_max3_f32 v165, v165, v166, v90
	v_sub_f32_e32 v166, v90, v165
	v_exp_f32_e32 v166, v166
	v_mov_b32_e32 v90, v165
	s_nop 0
	v_mul_f32_e32 v80, v80, v166
	v_mul_f32_e32 v81, v81, v166
	v_mul_f32_e32 v82, v82, v166
	v_mul_f32_e32 v83, v83, v166
	v_mul_f32_e32 v40, v40, v166
	v_mul_f32_e32 v41, v41, v166
	v_mul_f32_e32 v42, v42, v166
	v_mul_f32_e32 v43, v43, v166
	v_mul_f32_e32 v44, v44, v166
	v_mul_f32_e32 v45, v45, v166
	v_mul_f32_e32 v46, v46, v166
	v_mul_f32_e32 v47, v47, v166
	v_mul_f32_e32 v48, v48, v166
	v_mul_f32_e32 v49, v49, v166
	v_mul_f32_e32 v50, v50, v166
	v_mul_f32_e32 v51, v51, v166
	v_mul_f32_e32 v52, v52, v166
	v_mul_f32_e32 v53, v53, v166
	v_mul_f32_e32 v54, v54, v166
	v_mul_f32_e32 v55, v55, v166
.La0_nors_5:
	v_sub_f32_e32 v156, v156, v90
	v_sub_f32_e32 v157, v157, v90
	v_sub_f32_e32 v158, v158, v90
	v_sub_f32_e32 v159, v159, v90
	v_sub_f32_e32 v160, v160, v90
	v_sub_f32_e32 v161, v161, v90
	v_sub_f32_e32 v162, v162, v90
	v_sub_f32_e32 v163, v163, v90
	v_exp_f32_e32 v156, v156
	v_exp_f32_e32 v157, v157
	v_exp_f32_e32 v158, v158
	v_exp_f32_e32 v159, v159
	v_exp_f32_e32 v160, v160
	v_exp_f32_e32 v161, v161
	v_exp_f32_e32 v162, v162
	v_exp_f32_e32 v163, v163
	s_nop 0
	v_cvt_pk_bf16_f32 v172, v156, v157
	v_cvt_pk_bf16_f32 v173, v158, v159
	v_cvt_pk_bf16_f32 v174, v160, v161
	v_cvt_pk_bf16_f32 v175, v162, v163
	s_nop 1
	v_mfma_f32_16x16x32_bf16 v[40:43], v[140:143], v[172:175], v[40:43]
	v_mfma_f32_16x16x32_bf16 v[44:47], v[144:147], v[172:175], v[44:47]
	v_mfma_f32_16x16x32_bf16 v[48:51], v[148:151], v[172:175], v[48:51]
	v_mfma_f32_16x16x32_bf16 v[52:55], v[152:155], v[172:175], v[52:55]
	v_mfma_f32_16x16x32_bf16 v[80:83], v[176:179], v[172:175], v[80:83]
	s_branch .La0_pairdone_a1
.La0_notA_a1:
	s_cmp_lg_u32 s7, 0
	s_cbranch_scc0 .La0_pairdone_a1
	ds_read_b32 v156, v167 offset:0
	ds_read_b32 v157, v168 offset:0
	ds_read_b32 v158, v169 offset:0
	ds_read_b32 v159, v170 offset:0
	ds_read_b32 v160, v171 offset:0
	ds_read_b32 v161, v243 offset:0
	ds_read_b32 v162, v244 offset:0
	ds_read_b32 v163, v245 offset:0
	s_waitcnt lgkmcnt(0)
	v_mfma_f32_16x16x32_bf16 v[156:159], v[124:127], v[116:119], v[156:159]
	v_mfma_f32_16x16x32_bf16 v[160:163], v[132:135], v[116:119], v[160:163]
	v_mfma_f32_16x16x32_bf16 v[156:159], v[128:131], v[120:123], v[156:159]
	v_mfma_f32_16x16x32_bf16 v[160:163], v[136:139], v[120:123], v[160:163]
	v_add_f32_e32 v164, 0x41000000, v91
	s_nop 7
	s_nop 1
	v_max3_f32 v165, v156, v157, v158
	v_max3_f32 v166, v159, v160, v161
	v_max3_f32 v165, v165, v162, v163
	v_max_f32_e32 v165, v165, v166
	v_cmp_gt_f32_e32 vcc, v165, v164
	s_cbranch_vccz .La0_nors_6
	ds_bpermute_b32 v166, v194, v165
	s_waitcnt lgkmcnt(0)
	v_max_f32_e32 v165, v165, v166
	ds_bpermute_b32 v166, v195, v165
	s_waitcnt lgkmcnt(0)
	v_max3_f32 v165, v165, v166, v91
	v_sub_f32_e32 v166, v91, v165
	v_exp_f32_e32 v166, v166
	v_mov_b32_e32 v91, v165
	s_nop 0
	v_mul_f32_e32 v84, v84, v166
	v_mul_f32_e32 v85, v85, v166
	v_mul_f32_e32 v86, v86, v166
	v_mul_f32_e32 v87, v87, v166
	v_mul_f32_e32 v56, v56, v166
	v_mul_f32_e32 v57, v57, v166
	v_mul_f32_e32 v58, v58, v166
	v_mul_f32_e32 v59, v59, v166
	v_mul_f32_e32 v60, v60, v166
	v_mul_f32_e32 v61, v61, v166
	v_mul_f32_e32 v62, v62, v166
	v_mul_f32_e32 v63, v63, v166
	v_mul_f32_e32 v64, v64, v166
	v_mul_f32_e32 v65, v65, v166
	v_mul_f32_e32 v66, v66, v166
	v_mul_f32_e32 v67, v67, v166
	v_mul_f32_e32 v68, v68, v166
	v_mul_f32_e32 v69, v69, v166
	v_mul_f32_e32 v70, v70, v166
	v_mul_f32_e32 v71, v71, v166
.La0_nors_6:
	v_sub_f32_e32 v156, v156, v91
	v_sub_f32_e32 v157, v157, v91
	v_sub_f32_e32 v158, v158, v91
	v_sub_f32_e32 v159, v159, v91
	v_sub_f32_e32 v160, v160, v91
	v_sub_f32_e32 v161, v161, v91
	v_sub_f32_e32 v162, v162, v91
	v_sub_f32_e32 v163, v163, v91
	v_exp_f32_e32 v156, v156
	v_exp_f32_e32 v157, v157
	v_exp_f32_e32 v158, v158
	v_exp_f32_e32 v159, v159
	v_exp_f32_e32 v160, v160
	v_exp_f32_e32 v161, v161
	v_exp_f32_e32 v162, v162
	v_exp_f32_e32 v163, v163
	s_nop 0
	v_cvt_pk_bf16_f32 v172, v156, v157
	v_cvt_pk_bf16_f32 v173, v158, v159
	v_cvt_pk_bf16_f32 v174, v160, v161
	v_cvt_pk_bf16_f32 v175, v162, v163
	s_nop 1
	v_mfma_f32_16x16x32_bf16 v[56:59], v[140:143], v[172:175], v[56:59]
	v_mfma_f32_16x16x32_bf16 v[60:63], v[144:147], v[172:175], v[60:63]
	v_mfma_f32_16x16x32_bf16 v[64:67], v[148:151], v[172:175], v[64:67]
	v_mfma_f32_16x16x32_bf16 v[68:71], v[152:155], v[172:175], v[68:71]
	v_mfma_f32_16x16x32_bf16 v[84:87], v[176:179], v[172:175], v[84:87]
.La0_pairdone_a1:
.La0_k0done:
	s_lshl_b32 s60, s44, 1
	s_add_i32 s60, s60, s42
	s_add_i32 s60, s60, 1
	s_cmp_gt_i32 s60, s43
	s_cbranch_scc1 .La0_ss_done
	s_cmp_lt_i32 s60, s47
	s_cbranch_scc1 .La0_ss_done
	s_add_i32 s0, s50, 7
	s_cmp_gt_i32 s60, s0
	s_cbranch_scc1 .La0_ss_done
	s_and_b32 s61, s62, 1
	s_lshl_b32 s61, s61, 15
	s_add_i32 s61, s61, 0x4000
	v_add_u32_e32 v207, s61, v188
	v_add_u32_e32 v208, s61, v189
	v_add_u32_e32 v209, s61, v190
	ds_read_b128 v[124:127], v207
	ds_read_b128 v[132:135], v207 offset:512
	ds_read_b128 v[128:131], v208
	ds_read_b128 v[136:139], v208 offset:512
	ds_read_b128 v[140:143], v209 offset:0
	ds_read_b128 v[144:147], v209 offset:512
	ds_read_b128 v[148:151], v209 offset:1024
	ds_read_b128 v[152:155], v209 offset:1536
	s_sub_i32 s0, s60, s41
	s_sub_i32 s0, s0, s54
	s_add_i32 s0, s0, 1
	s_lshl_b32 s0, s0, 7
	v_add_u32_e32 v167, s0, v180
	v_add_u32_e32 v168, s0, v181
	v_add_u32_e32 v169, s0, v182
	v_add_u32_e32 v170, s0, v183
	v_add_u32_e32 v171, s0, v184
	v_add_u32_e32 v243, s0, v185
	v_add_u32_e32 v244, s0, v186
	v_add_u32_e32 v245, s0, v187
	s_sub_i32 s0, s60, s47
	s_cmp_le_u32 s0, 7
	s_cselect_b32 s6, 1, 0
	s_sub_i32 s0, s60, s48
	s_cmp_le_u32 s0, 7
	s_cselect_b32 s7, 1, 0
	s_and_b32 s0, s6, s7
	s_cmp_lg_u32 s0, 0
	s_cbranch_scc0 .La0_notboth_b0
	ds_read_b32 v156, v167 offset:768
	ds_read_b32 v157, v168 offset:768
	ds_read_b32 v158, v169 offset:768
	ds_read_b32 v159, v170 offset:768
	ds_read_b32 v160, v171 offset:768
	ds_read_b32 v161, v243 offset:768
	ds_read_b32 v162, v244 offset:768
	ds_read_b32 v163, v245 offset:768
	ds_read_b32 v232, v167 offset:512
	ds_read_b32 v233, v168 offset:512
	ds_read_b32 v234, v169 offset:512
	ds_read_b32 v235, v170 offset:512
	ds_read_b32 v236, v171 offset:512
	ds_read_b32 v237, v243 offset:512
	ds_read_b32 v238, v244 offset:512
	ds_read_b32 v239, v245 offset:512
	s_waitcnt lgkmcnt(8)
	v_mfma_f32_16x16x32_bf16 v[156:159], v[124:127], v[92:95], v[156:159]
	v_mfma_f32_16x16x32_bf16 v[160:163], v[132:135], v[92:95], v[160:163]
	s_waitcnt lgkmcnt(0)
	v_mfma_f32_16x16x32_bf16 v[232:235], v[124:127], v[100:103], v[232:235]
	v_mfma_f32_16x16x32_bf16 v[236:239], v[132:135], v[100:103], v[236:239]
	v_mfma_f32_16x16x32_bf16 v[156:159], v[128:131], v[96:99], v[156:159]
	v_mfma_f32_16x16x32_bf16 v[160:163], v[136:139], v[96:99], v[160:163]
	v_mfma_f32_16x16x32_bf16 v[232:235], v[128:131], v[104:107], v[232:235]
	v_mfma_f32_16x16x32_bf16 v[236:239], v[136:139], v[104:107], v[236:239]
	v_add_f32_e32 v164, 0x41000000, v88
	v_add_f32_e32 v240, 0x41000000, v89
	s_nop 4
	v_max3_f32 v165, v156, v157, v158
	v_max3_f32 v166, v159, v160, v161
	v_max3_f32 v165, v165, v162, v163
	v_max_f32_e32 v165, v165, v166
	v_max3_f32 v241, v232, v233, v234
	v_max3_f32 v242, v235, v236, v237
	v_max3_f32 v241, v241, v238, v239
	v_max_f32_e32 v241, v241, v242
	v_cmp_gt_f32_e32 vcc, v165, v164
	v_cmp_gt_f32_e64 s[0:1], v241, v240
	s_or_b64 vcc, vcc, s[0:1]
	s_cbranch_vccz .La0_pnors_7
	ds_bpermute_b32 v166, v194, v165
	ds_bpermute_b32 v242, v194, v241
	s_waitcnt lgkmcnt(0)
	v_max_f32_e32 v165, v165, v166
	v_max_f32_e32 v241, v241, v242
	ds_bpermute_b32 v166, v195, v165
	ds_bpermute_b32 v242, v195, v241
	s_waitcnt lgkmcnt(0)
	v_max3_f32 v165, v165, v166, v88
	v_max3_f32 v241, v241, v242, v89
	v_sub_f32_e32 v166, v88, v165
	v_sub_f32_e32 v242, v89, v241
	v_exp_f32_e32 v166, v166
	v_exp_f32_e32 v242, v242
	v_mov_b32_e32 v88, v165
	v_mov_b32_e32 v89, v241
	v_mul_f32_e32 v72, v72, v166
	v_mul_f32_e32 v73, v73, v166
	v_mul_f32_e32 v74, v74, v166
	v_mul_f32_e32 v75, v75, v166
	v_mul_f32_e32 v8, v8, v166
	v_mul_f32_e32 v9, v9, v166
	v_mul_f32_e32 v10, v10, v166
	v_mul_f32_e32 v11, v11, v166
	v_mul_f32_e32 v12, v12, v166
	v_mul_f32_e32 v13, v13, v166
	v_mul_f32_e32 v14, v14, v166
	v_mul_f32_e32 v15, v15, v166
	v_mul_f32_e32 v16, v16, v166
	v_mul_f32_e32 v17, v17, v166
	v_mul_f32_e32 v18, v18, v166
	v_mul_f32_e32 v19, v19, v166
	v_mul_f32_e32 v20, v20, v166
	v_mul_f32_e32 v21, v21, v166
	v_mul_f32_e32 v22, v22, v166
	v_mul_f32_e32 v23, v23, v166
	v_mul_f32_e32 v76, v76, v242
	v_mul_f32_e32 v77, v77, v242
	v_mul_f32_e32 v78, v78, v242
	v_mul_f32_e32 v79, v79, v242
	v_mul_f32_e32 v24, v24, v242
	v_mul_f32_e32 v25, v25, v242
	v_mul_f32_e32 v26, v26, v242
	v_mul_f32_e32 v27, v27, v242
	v_mul_f32_e32 v28, v28, v242
	v_mul_f32_e32 v29, v29, v242
	v_mul_f32_e32 v30, v30, v242
	v_mul_f32_e32 v31, v31, v242
	v_mul_f32_e32 v32, v32, v242
	v_mul_f32_e32 v33, v33, v242
	v_mul_f32_e32 v34, v34, v242
	v_mul_f32_e32 v35, v35, v242
	v_mul_f32_e32 v36, v36, v242
	v_mul_f32_e32 v37, v37, v242
	v_mul_f32_e32 v38, v38, v242
	v_mul_f32_e32 v39, v39, v242

.La0_pairdone_b1:
.La0_ss_done:
	s_add_i32 s62, s62, 1
	s_add_i32 s44, s44, 1
	s_cmp_lt_u32 s44, s45
	s_cbranch_scc1 .La0_ss
	s_add_i32 s5, s41, s54
	s_add_i32 s5, s5, 4
	s_lshl_b32 s5, s5, 17
	s_add_u32 s0, s56, s5
	s_addc_u32 s1, s57, 0
	global_load_dwordx4 v[124:127], v196, s[0:1] nt
	global_load_dwordx4 v[128:131], v196, s[0:1] offset:16 nt
	s_add_i32 s5, s41, s54
	s_add_i32 s5, s5, 6
	s_lshl_b32 s5, s5, 17
	s_add_u32 s0, s56, s5
	s_addc_u32 s1, s57, 0
	global_load_dwordx4 v[132:135], v196, s[0:1] nt
	global_load_dwordx4 v[136:139], v196, s[0:1] offset:16 nt
	s_cmp_lt_u32 s63, 1
	s_cbranch_scc0 .La0_last_round
	s_add_i32 s98, s41, 8
	s_add_i32 s5, s98, s54
	s_add_i32 s5, s5, 0
	s_lshl_b32 s5, s5, 6
	s_lshl_b32 s6, s53, 4
	s_add_i32 s5, s5, s6
	s_lshl_b32 s5, s5, 7
	s_add_u32 s0, s30, s5
	s_addc_u32 s1, s31, 0
	global_load_dwordx4 v[92:95], v193, s[0:1]
	global_load_dwordx4 v[96:99], v193, s[0:1] offset:16
	s_add_i32 s5, s98, s54
	s_add_i32 s5, s5, 2
	s_lshl_b32 s5, s5, 6
	s_lshl_b32 s6, s53, 4
	s_add_i32 s5, s5, s6
	s_lshl_b32 s5, s5, 7
	s_add_u32 s0, s30, s5
	s_addc_u32 s1, s31, 0
	global_load_dwordx4 v[100:103], v193, s[0:1]
	global_load_dwordx4 v[104:107], v193, s[0:1] offset:16
	s_add_i32 s5, s98, s54
	s_add_i32 s5, s5, 4
	s_lshl_b32 s5, s5, 6
	s_lshl_b32 s6, s53, 4
	s_add_i32 s5, s5, s6
	s_lshl_b32 s5, s5, 7
	s_add_u32 s0, s30, s5
	s_addc_u32 s1, s31, 0
	global_load_dwordx4 v[108:111], v193, s[0:1]
	global_load_dwordx4 v[112:115], v193, s[0:1] offset:16
	s_add_i32 s5, s98, s54
	s_add_i32 s5, s5, 6
	s_lshl_b32 s5, s5, 6
	s_lshl_b32 s6, s53, 4
	s_add_i32 s5, s5, s6
	s_lshl_b32 s5, s5, 7
	s_add_u32 s0, s30, s5
	s_addc_u32 s1, s31, 0
	global_load_dwordx4 v[116:119], v193, s[0:1]
	global_load_dwordx4 v[120:123], v193, s[0:1] offset:16
	s_waitcnt vmcnt(12)
.La0_dummy0:
	v_rcp_f32_e32 v172, v72
	v_lshlrev_b32_e32 v156, 16, v210
	v_and_b32_e32 v157, 0xffff0000, v210
	v_lshlrev_b32_e32 v158, 16, v211
	v_and_b32_e32 v159, 0xffff0000, v211
	v_mul_f32_e32 v160, 0xbfb8aa3b, v156
	v_mul_f32_e32 v161, 0xbfb8aa3b, v157
	v_mul_f32_e32 v162, 0xbfb8aa3b, v158
	v_mul_f32_e32 v163, 0xbfb8aa3b, v159
	v_exp_f32_e32 v160, v160
	v_exp_f32_e32 v161, v161
	v_exp_f32_e32 v162, v162
	v_exp_f32_e32 v163, v163
	s_nop 0
	v_add_f32_e32 v160, 1.0, v160
	v_add_f32_e32 v161, 1.0, v161
	v_add_f32_e32 v162, 1.0, v162
	v_add_f32_e32 v163, 1.0, v163
	v_rcp_f32_e32 v160, v160
	v_rcp_f32_e32 v161, v161
	v_rcp_f32_e32 v162, v162
	v_rcp_f32_e32 v163, v163
	s_nop 0
	v_mul_f32_e32 v156, v156, v160
	v_mul_f32_e32 v8, v8, v172
	v_mul_f32_e32 v157, v157, v161
	v_mul_f32_e32 v9, v9, v172
	v_mul_f32_e32 v158, v158, v162
	v_mul_f32_e32 v10, v10, v172
	v_mul_f32_e32 v159, v159, v163
	v_mul_f32_e32 v11, v11, v172
	v_mul_f32_e32 v8, v8, v156
	v_mul_f32_e32 v9, v9, v157
	v_mul_f32_e32 v10, v10, v158
	v_mul_f32_e32 v11, v11, v159
	v_cvt_pk_bf16_f32 v164, v8, v9
	v_cvt_pk_bf16_f32 v165, v10, v11
	v_lshlrev_b32_e32 v156, 16, v212
	v_and_b32_e32 v157, 0xffff0000, v212
	v_lshlrev_b32_e32 v158, 16, v213
	v_and_b32_e32 v159, 0xffff0000, v213
	v_mul_f32_e32 v160, 0xbfb8aa3b, v156
	v_mul_f32_e32 v161, 0xbfb8aa3b, v157
	v_mul_f32_e32 v162, 0xbfb8aa3b, v158
	v_mul_f32_e32 v163, 0xbfb8aa3b, v159
	v_exp_f32_e32 v160, v160
	v_exp_f32_e32 v161, v161
	v_exp_f32_e32 v162, v162
	v_exp_f32_e32 v163, v163
	s_nop 0
	v_add_f32_e32 v160, 1.0, v160
	v_add_f32_e32 v161, 1.0, v161
	v_add_f32_e32 v162, 1.0, v162
	v_add_f32_e32 v163, 1.0, v163
	v_rcp_f32_e32 v160, v160
	v_rcp_f32_e32 v161, v161
	v_rcp_f32_e32 v162, v162
	v_rcp_f32_e32 v163, v163
	s_nop 0
	v_mul_f32_e32 v156, v156, v160
	v_mul_f32_e32 v12, v12, v172
	v_mul_f32_e32 v157, v157, v161
	v_mul_f32_e32 v13, v13, v172
	v_mul_f32_e32 v158, v158, v162
	v_mul_f32_e32 v14, v14, v172
	v_mul_f32_e32 v159, v159, v163
	v_mul_f32_e32 v15, v15, v172
	v_mul_f32_e32 v12, v12, v156
	v_mul_f32_e32 v13, v13, v157
	v_mul_f32_e32 v14, v14, v158
	v_mul_f32_e32 v15, v15, v159
	v_cvt_pk_bf16_f32 v166, v12, v13
	v_cvt_pk_bf16_f32 v167, v14, v15
	v_lshlrev_b32_e32 v156, 16, v214
	v_and_b32_e32 v157, 0xffff0000, v214
	v_lshlrev_b32_e32 v158, 16, v215
	v_and_b32_e32 v159, 0xffff0000, v215
	v_mul_f32_e32 v160, 0xbfb8aa3b, v156
	v_mul_f32_e32 v161, 0xbfb8aa3b, v157
	v_mul_f32_e32 v162, 0xbfb8aa3b, v158
	v_mul_f32_e32 v163, 0xbfb8aa3b, v159
	v_exp_f32_e32 v160, v160
	v_exp_f32_e32 v161, v161
	v_exp_f32_e32 v162, v162
	v_exp_f32_e32 v163, v163
	s_nop 0
	v_add_f32_e32 v160, 1.0, v160
	v_add_f32_e32 v161, 1.0, v161
	v_add_f32_e32 v162, 1.0, v162
	v_add_f32_e32 v163, 1.0, v163
	v_rcp_f32_e32 v160, v160
	v_rcp_f32_e32 v161, v161
	v_rcp_f32_e32 v162, v162
	v_rcp_f32_e32 v163, v163
	s_nop 0
	v_mul_f32_e32 v156, v156, v160
	v_mul_f32_e32 v16, v16, v172
	v_mul_f32_e32 v157, v157, v161
	v_mul_f32_e32 v17, v17, v172
	v_mul_f32_e32 v158, v158, v162
	v_mul_f32_e32 v18, v18, v172
	v_mul_f32_e32 v159, v159, v163
	v_mul_f32_e32 v19, v19, v172
	v_mul_f32_e32 v16, v16, v156
	v_mul_f32_e32 v17, v17, v157
	v_mul_f32_e32 v18, v18, v158
	v_mul_f32_e32 v19, v19, v159
	v_cvt_pk_bf16_f32 v168, v16, v17
	v_cvt_pk_bf16_f32 v169, v18, v19
	v_lshlrev_b32_e32 v156, 16, v216
	v_and_b32_e32 v157, 0xffff0000, v216
	v_lshlrev_b32_e32 v158, 16, v217
	v_and_b32_e32 v159, 0xffff0000, v217
	v_mul_f32_e32 v160, 0xbfb8aa3b, v156
	v_mul_f32_e32 v161, 0xbfb8aa3b, v157
	v_mul_f32_e32 v162, 0xbfb8aa3b, v158
	v_mul_f32_e32 v163, 0xbfb8aa3b, v159
	v_exp_f32_e32 v160, v160
	v_exp_f32_e32 v161, v161
	v_exp_f32_e32 v162, v162
	v_exp_f32_e32 v163, v163
	s_nop 0
	v_add_f32_e32 v160, 1.0, v160
	v_add_f32_e32 v161, 1.0, v161
	v_add_f32_e32 v162, 1.0, v162
	v_add_f32_e32 v163, 1.0, v163
	v_rcp_f32_e32 v160, v160
	v_rcp_f32_e32 v161, v161
	v_rcp_f32_e32 v162, v162
	v_rcp_f32_e32 v163, v163
	s_nop 0
	v_mul_f32_e32 v156, v156, v160
	v_mul_f32_e32 v20, v20, v172
	v_mul_f32_e32 v157, v157, v161
	v_mul_f32_e32 v21, v21, v172
	v_mul_f32_e32 v158, v158, v162
	v_mul_f32_e32 v22, v22, v172
	v_mul_f32_e32 v159, v159, v163
	v_mul_f32_e32 v23, v23, v172
	v_mul_f32_e32 v20, v20, v156
	v_mul_f32_e32 v21, v21, v157
	v_mul_f32_e32 v22, v22, v158
	v_mul_f32_e32 v23, v23, v159
	v_cvt_pk_bf16_f32 v170, v20, v21
	v_cvt_pk_bf16_f32 v171, v22, v23
	s_add_i32 s5, s41, s54
	s_add_i32 s5, s5, 0
	s_lshl_b32 s5, s5, 17
	s_add_u32 s0, s58, s5
	s_addc_u32 s1, s59, 0
	global_store_dwordx4 v196, v[164:167], s[0:1]
	global_store_dwordx4 v196, v[168:171], s[0:1] offset:16
	s_nop 1
	v_rcp_f32_e32 v172, v76
	v_lshlrev_b32_e32 v156, 16, v218
	v_and_b32_e32 v157, 0xffff0000, v218
	v_lshlrev_b32_e32 v158, 16, v219
	v_and_b32_e32 v159, 0xffff0000, v219
	v_mul_f32_e32 v160, 0xbfb8aa3b, v156
	v_mul_f32_e32 v161, 0xbfb8aa3b, v157
	v_mul_f32_e32 v162, 0xbfb8aa3b, v158
	v_mul_f32_e32 v163, 0xbfb8aa3b, v159
	v_exp_f32_e32 v160, v160
	v_exp_f32_e32 v161, v161
	v_exp_f32_e32 v162, v162
	v_exp_f32_e32 v163, v163
	s_nop 0
	v_add_f32_e32 v160, 1.0, v160
	v_add_f32_e32 v161, 1.0, v161
	v_add_f32_e32 v162, 1.0, v162
	v_add_f32_e32 v163, 1.0, v163
	v_rcp_f32_e32 v160, v160
	v_rcp_f32_e32 v161, v161
	v_rcp_f32_e32 v162, v162
	v_rcp_f32_e32 v163, v163
	s_nop 0
	v_mul_f32_e32 v156, v156, v160
	v_mul_f32_e32 v24, v24, v172
	v_mul_f32_e32 v157, v157, v161
	v_mul_f32_e32 v25, v25, v172
	v_mul_f32_e32 v158, v158, v162
	v_mul_f32_e32 v26, v26, v172
	v_mul_f32_e32 v159, v159, v163
	v_mul_f32_e32 v27, v27, v172
	v_mul_f32_e32 v24, v24, v156
	v_mul_f32_e32 v25, v25, v157
	v_mul_f32_e32 v26, v26, v158
	v_mul_f32_e32 v27, v27, v159
	v_cvt_pk_bf16_f32 v164, v24, v25
	v_cvt_pk_bf16_f32 v165, v26, v27
	v_lshlrev_b32_e32 v156, 16, v220
	v_and_b32_e32 v157, 0xffff0000, v220
	v_lshlrev_b32_e32 v158, 16, v221
	v_and_b32_e32 v159, 0xffff0000, v221
	v_mul_f32_e32 v160, 0xbfb8aa3b, v156
	v_mul_f32_e32 v161, 0xbfb8aa3b, v157
	v_mul_f32_e32 v162, 0xbfb8aa3b, v158
	v_mul_f32_e32 v163, 0xbfb8aa3b, v159
	v_exp_f32_e32 v160, v160
	v_exp_f32_e32 v161, v161
	v_exp_f32_e32 v162, v162
	v_exp_f32_e32 v163, v163
	s_nop 0
	v_add_f32_e32 v160, 1.0, v160
	v_add_f32_e32 v161, 1.0, v161
	v_add_f32_e32 v162, 1.0, v162
	v_add_f32_e32 v163, 1.0, v163
	v_rcp_f32_e32 v160, v160
	v_rcp_f32_e32 v161, v161
	v_rcp_f32_e32 v162, v162
	v_rcp_f32_e32 v163, v163
	s_nop 0
	v_mul_f32_e32 v156, v156, v160
	v_mul_f32_e32 v28, v28, v172
	v_mul_f32_e32 v157, v157, v161
	v_mul_f32_e32 v29, v29, v172
	v_mul_f32_e32 v158, v158, v162
	v_mul_f32_e32 v30, v30, v172
	v_mul_f32_e32 v159, v159, v163
	v_mul_f32_e32 v31, v31, v172
	v_mul_f32_e32 v28, v28, v156
	v_mul_f32_e32 v29, v29, v157
	v_mul_f32_e32 v30, v30, v158
	v_mul_f32_e32 v31, v31, v159
	v_cvt_pk_bf16_f32 v166, v28, v29
	v_cvt_pk_bf16_f32 v167, v30, v31
	v_lshlrev_b32_e32 v156, 16, v222
	v_and_b32_e32 v157, 0xffff0000, v222
	v_lshlrev_b32_e32 v158, 16, v223
	v_and_b32_e32 v159, 0xffff0000, v223
	v_mul_f32_e32 v160, 0xbfb8aa3b, v156
	v_mul_f32_e32 v161, 0xbfb8aa3b, v157
	v_mul_f32_e32 v162, 0xbfb8aa3b, v158
	v_mul_f32_e32 v163, 0xbfb8aa3b, v159
	v_exp_f32_e32 v160, v160
	v_exp_f32_e32 v161, v161
	v_exp_f32_e32 v162, v162
	v_exp_f32_e32 v163, v163
	s_nop 0
	v_add_f32_e32 v160, 1.0, v160
	v_add_f32_e32 v161, 1.0, v161
	v_add_f32_e32 v162, 1.0, v162
	v_add_f32_e32 v163, 1.0, v163
	v_rcp_f32_e32 v160, v160
	v_rcp_f32_e32 v161, v161
	v_rcp_f32_e32 v162, v162
	v_rcp_f32_e32 v163, v163
	s_nop 0
	v_mul_f32_e32 v156, v156, v160
	v_mul_f32_e32 v32, v32, v172
	v_mul_f32_e32 v157, v157, v161
	v_mul_f32_e32 v33, v33, v172
	v_mul_f32_e32 v158, v158, v162
	v_mul_f32_e32 v34, v34, v172
	v_mul_f32_e32 v159, v159, v163
	v_mul_f32_e32 v35, v35, v172
	v_mul_f32_e32 v32, v32, v156
	v_mul_f32_e32 v33, v33, v157
	v_mul_f32_e32 v34, v34, v158
	v_mul_f32_e32 v35, v35, v159
	v_cvt_pk_bf16_f32 v168, v32, v33
	v_cvt_pk_bf16_f32 v169, v34, v35
	v_lshlrev_b32_e32 v156, 16, v224
	v_and_b32_e32 v157, 0xffff0000, v224
	v_lshlrev_b32_e32 v158, 16, v225
	v_and_b32_e32 v159, 0xffff0000, v225
	v_mul_f32_e32 v160, 0xbfb8aa3b, v156
	v_mul_f32_e32 v161, 0xbfb8aa3b, v157
	v_mul_f32_e32 v162, 0xbfb8aa3b, v158
	v_mul_f32_e32 v163, 0xbfb8aa3b, v159
	v_exp_f32_e32 v160, v160
	v_exp_f32_e32 v161, v161
	v_exp_f32_e32 v162, v162
	v_exp_f32_e32 v163, v163
	s_nop 0
	v_add_f32_e32 v160, 1.0, v160
	v_add_f32_e32 v161, 1.0, v161
	v_add_f32_e32 v162, 1.0, v162
	v_add_f32_e32 v163, 1.0, v163
	v_rcp_f32_e32 v160, v160
	v_rcp_f32_e32 v161, v161
	v_rcp_f32_e32 v162, v162
	v_rcp_f32_e32 v163, v163
	s_nop 0
	v_mul_f32_e32 v156, v156, v160
	v_mul_f32_e32 v36, v36, v172
	v_mul_f32_e32 v157, v157, v161
	v_mul_f32_e32 v37, v37, v172
	v_mul_f32_e32 v158, v158, v162
	v_mul_f32_e32 v38, v38, v172
	v_mul_f32_e32 v159, v159, v163
	v_mul_f32_e32 v39, v39, v172
	v_mul_f32_e32 v36, v36, v156
	v_mul_f32_e32 v37, v37, v157
	v_mul_f32_e32 v38, v38, v158
	v_mul_f32_e32 v39, v39, v159
	v_cvt_pk_bf16_f32 v170, v36, v37
	v_cvt_pk_bf16_f32 v171, v38, v39
	s_add_i32 s5, s41, s54
	s_add_i32 s5, s5, 2
	s_lshl_b32 s5, s5, 17
	s_add_u32 s0, s58, s5
	s_addc_u32 s1, s59, 0
	global_store_dwordx4 v196, v[164:167], s[0:1]
	global_store_dwordx4 v196, v[168:171], s[0:1] offset:16
	s_nop 1
	s_waitcnt vmcnt(12)
	v_rcp_f32_e32 v172, v80
	v_lshlrev_b32_e32 v156, 16, v124
	v_and_b32_e32 v157, 0xffff0000, v124
	v_lshlrev_b32_e32 v158, 16, v125
	v_and_b32_e32 v159, 0xffff0000, v125
	v_mul_f32_e32 v160, 0xbfb8aa3b, v156
	v_mul_f32_e32 v161, 0xbfb8aa3b, v157
	v_mul_f32_e32 v162, 0xbfb8aa3b, v158
	v_mul_f32_e32 v163, 0xbfb8aa3b, v159
	v_exp_f32_e32 v160, v160
	v_exp_f32_e32 v161, v161
	v_exp_f32_e32 v162, v162
	v_exp_f32_e32 v163, v163
	s_nop 0
	v_add_f32_e32 v160, 1.0, v160
	v_add_f32_e32 v161, 1.0, v161
	v_add_f32_e32 v162, 1.0, v162
	v_add_f32_e32 v163, 1.0, v163
	v_rcp_f32_e32 v160, v160
	v_rcp_f32_e32 v161, v161
	v_rcp_f32_e32 v162, v162
	v_rcp_f32_e32 v163, v163
	s_nop 0
	v_mul_f32_e32 v156, v156, v160
	v_mul_f32_e32 v40, v40, v172
	v_mul_f32_e32 v157, v157, v161
	v_mul_f32_e32 v41, v41, v172
	v_mul_f32_e32 v158, v158, v162
	v_mul_f32_e32 v42, v42, v172
	v_mul_f32_e32 v159, v159, v163
	v_mul_f32_e32 v43, v43, v172
	v_mul_f32_e32 v40, v40, v156
	v_mul_f32_e32 v41, v41, v157
	v_mul_f32_e32 v42, v42, v158
	v_mul_f32_e32 v43, v43, v159
	v_cvt_pk_bf16_f32 v164, v40, v41
	v_cvt_pk_bf16_f32 v165, v42, v43
	v_lshlrev_b32_e32 v156, 16, v126
	v_and_b32_e32 v157, 0xffff0000, v126
	v_lshlrev_b32_e32 v158, 16, v127
	v_and_b32_e32 v159, 0xffff0000, v127
	v_mul_f32_e32 v160, 0xbfb8aa3b, v156
	v_mul_f32_e32 v161, 0xbfb8aa3b, v157
	v_mul_f32_e32 v162, 0xbfb8aa3b, v158
	v_mul_f32_e32 v163, 0xbfb8aa3b, v159
	v_exp_f32_e32 v160, v160
	v_exp_f32_e32 v161, v161
	v_exp_f32_e32 v162, v162
	v_exp_f32_e32 v163, v163
	s_nop 0
	v_add_f32_e32 v160, 1.0, v160
	v_add_f32_e32 v161, 1.0, v161
	v_add_f32_e32 v162, 1.0, v162
	v_add_f32_e32 v163, 1.0, v163
	v_rcp_f32_e32 v160, v160
	v_rcp_f32_e32 v161, v161
	v_rcp_f32_e32 v162, v162
	v_rcp_f32_e32 v163, v163
	s_nop 0
	v_mul_f32_e32 v156, v156, v160
	v_mul_f32_e32 v44, v44, v172
	v_mul_f32_e32 v157, v157, v161
	v_mul_f32_e32 v45, v45, v172
	v_mul_f32_e32 v158, v158, v162
	v_mul_f32_e32 v46, v46, v172
	v_mul_f32_e32 v159, v159, v163
	v_mul_f32_e32 v47, v47, v172
	v_mul_f32_e32 v44, v44, v156
	v_mul_f32_e32 v45, v45, v157
	v_mul_f32_e32 v46, v46, v158
	v_mul_f32_e32 v47, v47, v159
	v_cvt_pk_bf16_f32 v166, v44, v45
	v_cvt_pk_bf16_f32 v167, v46, v47
	v_lshlrev_b32_e32 v156, 16, v128
	v_and_b32_e32 v157, 0xffff0000, v128
	v_lshlrev_b32_e32 v158, 16, v129
	v_and_b32_e32 v159, 0xffff0000, v129
	v_mul_f32_e32 v160, 0xbfb8aa3b, v156
	v_mul_f32_e32 v161, 0xbfb8aa3b, v157
	v_mul_f32_e32 v162, 0xbfb8aa3b, v158
	v_mul_f32_e32 v163, 0xbfb8aa3b, v159
	v_exp_f32_e32 v160, v160
	v_exp_f32_e32 v161, v161
	v_exp_f32_e32 v162, v162
	v_exp_f32_e32 v163, v163
	s_nop 0
	v_add_f32_e32 v160, 1.0, v160
	v_add_f32_e32 v161, 1.0, v161
	v_add_f32_e32 v162, 1.0, v162
	v_add_f32_e32 v163, 1.0, v163
	v_rcp_f32_e32 v160, v160
	v_rcp_f32_e32 v161, v161
	v_rcp_f32_e32 v162, v162
	v_rcp_f32_e32 v163, v163
	s_nop 0
	v_mul_f32_e32 v156, v156, v160
	v_mul_f32_e32 v48, v48, v172
	v_mul_f32_e32 v157, v157, v161
	v_mul_f32_e32 v49, v49, v172
	v_mul_f32_e32 v158, v158, v162
	v_mul_f32_e32 v50, v50, v172
	v_mul_f32_e32 v159, v159, v163
	v_mul_f32_e32 v51, v51, v172
	v_mul_f32_e32 v48, v48, v156
	v_mul_f32_e32 v49, v49, v157
	v_mul_f32_e32 v50, v50, v158
	v_mul_f32_e32 v51, v51, v159
	v_cvt_pk_bf16_f32 v168, v48, v49
	v_cvt_pk_bf16_f32 v169, v50, v51
	v_lshlrev_b32_e32 v156, 16, v130
	v_and_b32_e32 v157, 0xffff0000, v130
	v_lshlrev_b32_e32 v158, 16, v131
	v_and_b32_e32 v159, 0xffff0000, v131
	v_mul_f32_e32 v160, 0xbfb8aa3b, v156
	v_mul_f32_e32 v161, 0xbfb8aa3b, v157
	v_mul_f32_e32 v162, 0xbfb8aa3b, v158
	v_mul_f32_e32 v163, 0xbfb8aa3b, v159
	v_exp_f32_e32 v160, v160
	v_exp_f32_e32 v161, v161
	v_exp_f32_e32 v162, v162
	v_exp_f32_e32 v163, v163
	s_nop 0
	v_add_f32_e32 v160, 1.0, v160
	v_add_f32_e32 v161, 1.0, v161
	v_add_f32_e32 v162, 1.0, v162
	v_add_f32_e32 v163, 1.0, v163
	v_rcp_f32_e32 v160, v160
	v_rcp_f32_e32 v161, v161
	v_rcp_f32_e32 v162, v162
	v_rcp_f32_e32 v163, v163
	s_nop 0
	v_mul_f32_e32 v156, v156, v160
	v_mul_f32_e32 v52, v52, v172
	v_mul_f32_e32 v157, v157, v161
	v_mul_f32_e32 v53, v53, v172
	v_mul_f32_e32 v158, v158, v162
	v_mul_f32_e32 v54, v54, v172
	v_mul_f32_e32 v159, v159, v163
	v_mul_f32_e32 v55, v55, v172
	v_mul_f32_e32 v52, v52, v156
	v_mul_f32_e32 v53, v53, v157
	v_mul_f32_e32 v54, v54, v158
	v_mul_f32_e32 v55, v55, v159
	v_cvt_pk_bf16_f32 v170, v52, v53
	v_cvt_pk_bf16_f32 v171, v54, v55
	s_add_i32 s5, s41, s54
	s_add_i32 s5, s5, 4
	s_lshl_b32 s5, s5, 17
	s_add_u32 s0, s58, s5
	s_addc_u32 s1, s59, 0
	global_store_dwordx4 v196, v[164:167], s[0:1]
	global_store_dwordx4 v196, v[168:171], s[0:1] offset:16
	s_nop 1
	v_rcp_f32_e32 v172, v84
	v_lshlrev_b32_e32 v156, 16, v132
	v_and_b32_e32 v157, 0xffff0000, v132
	v_lshlrev_b32_e32 v158, 16, v133
	v_and_b32_e32 v159, 0xffff0000, v133
	v_mul_f32_e32 v160, 0xbfb8aa3b, v156
	v_mul_f32_e32 v161, 0xbfb8aa3b, v157
	v_mul_f32_e32 v162, 0xbfb8aa3b, v158
	v_mul_f32_e32 v163, 0xbfb8aa3b, v159
	v_exp_f32_e32 v160, v160
	v_exp_f32_e32 v161, v161
	v_exp_f32_e32 v162, v162
	v_exp_f32_e32 v163, v163
	s_nop 0
	v_add_f32_e32 v160, 1.0, v160
	v_add_f32_e32 v161, 1.0, v161
	v_add_f32_e32 v162, 1.0, v162
	v_add_f32_e32 v163, 1.0, v163
	v_rcp_f32_e32 v160, v160
	v_rcp_f32_e32 v161, v161
	v_rcp_f32_e32 v162, v162
	v_rcp_f32_e32 v163, v163
	s_nop 0
	v_mul_f32_e32 v156, v156, v160
	v_mul_f32_e32 v56, v56, v172
	v_mul_f32_e32 v157, v157, v161
	v_mul_f32_e32 v57, v57, v172
	v_mul_f32_e32 v158, v158, v162
	v_mul_f32_e32 v58, v58, v172
	v_mul_f32_e32 v159, v159, v163
	v_mul_f32_e32 v59, v59, v172
	v_mul_f32_e32 v56, v56, v156
	v_mul_f32_e32 v57, v57, v157
	v_mul_f32_e32 v58, v58, v158
	v_mul_f32_e32 v59, v59, v159
	v_cvt_pk_bf16_f32 v164, v56, v57
	v_cvt_pk_bf16_f32 v165, v58, v59
	v_lshlrev_b32_e32 v156, 16, v134
	v_and_b32_e32 v157, 0xffff0000, v134
	v_lshlrev_b32_e32 v158, 16, v135
	v_and_b32_e32 v159, 0xffff0000, v135
	v_mul_f32_e32 v160, 0xbfb8aa3b, v156
	v_mul_f32_e32 v161, 0xbfb8aa3b, v157
	v_mul_f32_e32 v162, 0xbfb8aa3b, v158
	v_mul_f32_e32 v163, 0xbfb8aa3b, v159
	v_exp_f32_e32 v160, v160
	v_exp_f32_e32 v161, v161
	v_exp_f32_e32 v162, v162
	v_exp_f32_e32 v163, v163
	s_nop 0
	v_add_f32_e32 v160, 1.0, v160
	v_add_f32_e32 v161, 1.0, v161
	v_add_f32_e32 v162, 1.0, v162
	v_add_f32_e32 v163, 1.0, v163
	v_rcp_f32_e32 v160, v160
	v_rcp_f32_e32 v161, v161
	v_rcp_f32_e32 v162, v162
	v_rcp_f32_e32 v163, v163
	s_nop 0
	v_mul_f32_e32 v156, v156, v160
	v_mul_f32_e32 v60, v60, v172
	v_mul_f32_e32 v157, v157, v161
	v_mul_f32_e32 v61, v61, v172
	v_mul_f32_e32 v158, v158, v162
	v_mul_f32_e32 v62, v62, v172
	v_mul_f32_e32 v159, v159, v163
	v_mul_f32_e32 v63, v63, v172
	v_mul_f32_e32 v60, v60, v156
	v_mul_f32_e32 v61, v61, v157
	v_mul_f32_e32 v62, v62, v158
	v_mul_f32_e32 v63, v63, v159
	v_cvt_pk_bf16_f32 v166, v60, v61
	v_cvt_pk_bf16_f32 v167, v62, v63
	v_lshlrev_b32_e32 v156, 16, v136
	v_and_b32_e32 v157, 0xffff0000, v136
	v_lshlrev_b32_e32 v158, 16, v137
	v_and_b32_e32 v159, 0xffff0000, v137
	v_mul_f32_e32 v160, 0xbfb8aa3b, v156
	v_mul_f32_e32 v161, 0xbfb8aa3b, v157
	v_mul_f32_e32 v162, 0xbfb8aa3b, v158
	v_mul_f32_e32 v163, 0xbfb8aa3b, v159
	v_exp_f32_e32 v160, v160
	v_exp_f32_e32 v161, v161
	v_exp_f32_e32 v162, v162
	v_exp_f32_e32 v163, v163
	s_nop 0
	v_add_f32_e32 v160, 1.0, v160
	v_add_f32_e32 v161, 1.0, v161
	v_add_f32_e32 v162, 1.0, v162
	v_add_f32_e32 v163, 1.0, v163
	v_rcp_f32_e32 v160, v160
	v_rcp_f32_e32 v161, v161
	v_rcp_f32_e32 v162, v162
	v_rcp_f32_e32 v163, v163
	s_nop 0
	v_mul_f32_e32 v156, v156, v160
	v_mul_f32_e32 v64, v64, v172
	v_mul_f32_e32 v157, v157, v161
	v_mul_f32_e32 v65, v65, v172
	v_mul_f32_e32 v158, v158, v162
	v_mul_f32_e32 v66, v66, v172
	v_mul_f32_e32 v159, v159, v163
	v_mul_f32_e32 v67, v67, v172
	v_mul_f32_e32 v64, v64, v156
	v_mul_f32_e32 v65, v65, v157
	v_mul_f32_e32 v66, v66, v158
	v_mul_f32_e32 v67, v67, v159
	v_cvt_pk_bf16_f32 v168, v64, v65
	v_cvt_pk_bf16_f32 v169, v66, v67
	v_lshlrev_b32_e32 v156, 16, v138
	v_and_b32_e32 v157, 0xffff0000, v138
	v_lshlrev_b32_e32 v158, 16, v139
	v_and_b32_e32 v159, 0xffff0000, v139
	v_mul_f32_e32 v160, 0xbfb8aa3b, v156
	v_mul_f32_e32 v161, 0xbfb8aa3b, v157
	v_mul_f32_e32 v162, 0xbfb8aa3b, v158
	v_mul_f32_e32 v163, 0xbfb8aa3b, v159
	v_exp_f32_e32 v160, v160
	v_exp_f32_e32 v161, v161
	v_exp_f32_e32 v162, v162
	v_exp_f32_e32 v163, v163
	s_nop 0
	v_add_f32_e32 v160, 1.0, v160
	v_add_f32_e32 v161, 1.0, v161
	v_add_f32_e32 v162, 1.0, v162
	v_add_f32_e32 v163, 1.0, v163
	v_rcp_f32_e32 v160, v160
	v_rcp_f32_e32 v161, v161
	v_rcp_f32_e32 v162, v162
	v_rcp_f32_e32 v163, v163
	s_nop 0
	v_mul_f32_e32 v156, v156, v160
	v_mul_f32_e32 v68, v68, v172
	v_mul_f32_e32 v157, v157, v161
	v_mul_f32_e32 v69, v69, v172
	v_mul_f32_e32 v158, v158, v162
	v_mul_f32_e32 v70, v70, v172
	v_mul_f32_e32 v159, v159, v163
	v_mul_f32_e32 v71, v71, v172
	v_mul_f32_e32 v68, v68, v156
	v_mul_f32_e32 v69, v69, v157
	v_mul_f32_e32 v70, v70, v158
	v_mul_f32_e32 v71, v71, v159
	v_cvt_pk_bf16_f32 v170, v68, v69
	v_cvt_pk_bf16_f32 v171, v70, v71
	s_add_i32 s5, s41, s54
	s_add_i32 s5, s5, 6
	s_lshl_b32 s5, s5, 17
	s_add_u32 s0, s58, s5
	s_addc_u32 s1, s59, 0
	global_store_dwordx4 v196, v[164:167], s[0:1]
	global_store_dwordx4 v196, v[168:171], s[0:1] offset:16
	s_nop 1
	s_add_i32 s63, s63, 1
	s_add_i32 s41, s41, 8
	s_add_i32 s42, s41, -4
	s_max_i32 s42, s42, 0
	s_min_i32 s42, s42, 0x78
	s_add_i32 s43, s41, 3
	s_max_i32 s43, s43, 0
	s_min_i32 s43, s43, 0x78
	s_add_i32 s43, s43, 7
	s_sub_i32 s45, s43, s42
	s_add_i32 s45, s45, 2
	s_lshr_b32 s45, s45, 1
	s_add_i32 s47, s41, s54
	s_add_i32 s47, s47, -4
	s_max_i32 s47, s47, 0
	s_min_i32 s47, s47, 0x78
	s_add_i32 s48, s41, s54
	s_add_i32 s48, s48, -2
	s_max_i32 s48, s48, 0
	s_min_i32 s48, s48, 0x78
	s_add_i32 s49, s41, s54
	s_add_i32 s49, s49, 0
	s_max_i32 s49, s49, 0
	s_min_i32 s49, s49, 0x78
	s_add_i32 s50, s41, s54
	s_add_i32 s50, s50, 2
	s_max_i32 s50, s50, 0
	s_min_i32 s50, s50, 0x78
	s_branch .La0_round
.La0_last_round:
	s_waitcnt vmcnt(4)
	v_rcp_f32_e32 v172, v72
	v_lshlrev_b32_e32 v156, 16, v210
	v_and_b32_e32 v157, 0xffff0000, v210
	v_lshlrev_b32_e32 v158, 16, v211
	v_and_b32_e32 v159, 0xffff0000, v211
	v_mul_f32_e32 v160, 0xbfb8aa3b, v156
	v_mul_f32_e32 v161, 0xbfb8aa3b, v157
	v_mul_f32_e32 v162, 0xbfb8aa3b, v158
	v_mul_f32_e32 v163, 0xbfb8aa3b, v159
	v_exp_f32_e32 v160, v160
	v_exp_f32_e32 v161, v161
	v_exp_f32_e32 v162, v162
	v_exp_f32_e32 v163, v163
	s_nop 0
	v_add_f32_e32 v160, 1.0, v160
	v_add_f32_e32 v161, 1.0, v161
	v_add_f32_e32 v162, 1.0, v162
	v_add_f32_e32 v163, 1.0, v163
	v_rcp_f32_e32 v160, v160
	v_rcp_f32_e32 v161, v161
	v_rcp_f32_e32 v162, v162
	v_rcp_f32_e32 v163, v163
	s_nop 0
	v_mul_f32_e32 v156, v156, v160
	v_mul_f32_e32 v8, v8, v172
	v_mul_f32_e32 v157, v157, v161
	v_mul_f32_e32 v9, v9, v172
	v_mul_f32_e32 v158, v158, v162
	v_mul_f32_e32 v10, v10, v172
	v_mul_f32_e32 v159, v159, v163
	v_mul_f32_e32 v11, v11, v172
	v_mul_f32_e32 v8, v8, v156
	v_mul_f32_e32 v9, v9, v157
	v_mul_f32_e32 v10, v10, v158
	v_mul_f32_e32 v11, v11, v159
	v_cvt_pk_bf16_f32 v164, v8, v9
	v_cvt_pk_bf16_f32 v165, v10, v11
	v_lshlrev_b32_e32 v156, 16, v212
	v_and_b32_e32 v157, 0xffff0000, v212
	v_lshlrev_b32_e32 v158, 16, v213
	v_and_b32_e32 v159, 0xffff0000, v213
	v_mul_f32_e32 v160, 0xbfb8aa3b, v156
	v_mul_f32_e32 v161, 0xbfb8aa3b, v157
	v_mul_f32_e32 v162, 0xbfb8aa3b, v158
	v_mul_f32_e32 v163, 0xbfb8aa3b, v159
	v_exp_f32_e32 v160, v160
	v_exp_f32_e32 v161, v161
	v_exp_f32_e32 v162, v162
	v_exp_f32_e32 v163, v163
	s_nop 0
	v_add_f32_e32 v160, 1.0, v160
	v_add_f32_e32 v161, 1.0, v161
	v_add_f32_e32 v162, 1.0, v162
	v_add_f32_e32 v163, 1.0, v163
	v_rcp_f32_e32 v160, v160
	v_rcp_f32_e32 v161, v161
	v_rcp_f32_e32 v162, v162
	v_rcp_f32_e32 v163, v163
	s_nop 0
	v_mul_f32_e32 v156, v156, v160
	v_mul_f32_e32 v12, v12, v172
	v_mul_f32_e32 v157, v157, v161
	v_mul_f32_e32 v13, v13, v172
	v_mul_f32_e32 v158, v158, v162
	v_mul_f32_e32 v14, v14, v172
	v_mul_f32_e32 v159, v159, v163
	v_mul_f32_e32 v15, v15, v172
	v_mul_f32_e32 v12, v12, v156
	v_mul_f32_e32 v13, v13, v157
	v_mul_f32_e32 v14, v14, v158
	v_mul_f32_e32 v15, v15, v159
	v_cvt_pk_bf16_f32 v166, v12, v13
	v_cvt_pk_bf16_f32 v167, v14, v15
	v_lshlrev_b32_e32 v156, 16, v214
	v_and_b32_e32 v157, 0xffff0000, v214
	v_lshlrev_b32_e32 v158, 16, v215
	v_and_b32_e32 v159, 0xffff0000, v215
	v_mul_f32_e32 v160, 0xbfb8aa3b, v156
	v_mul_f32_e32 v161, 0xbfb8aa3b, v157
	v_mul_f32_e32 v162, 0xbfb8aa3b, v158
	v_mul_f32_e32 v163, 0xbfb8aa3b, v159
	v_exp_f32_e32 v160, v160
	v_exp_f32_e32 v161, v161
	v_exp_f32_e32 v162, v162
	v_exp_f32_e32 v163, v163
	s_nop 0
	v_add_f32_e32 v160, 1.0, v160
	v_add_f32_e32 v161, 1.0, v161
	v_add_f32_e32 v162, 1.0, v162
	v_add_f32_e32 v163, 1.0, v163
	v_rcp_f32_e32 v160, v160
	v_rcp_f32_e32 v161, v161
	v_rcp_f32_e32 v162, v162
	v_rcp_f32_e32 v163, v163
	s_nop 0
	v_mul_f32_e32 v156, v156, v160
	v_mul_f32_e32 v16, v16, v172
	v_mul_f32_e32 v157, v157, v161
	v_mul_f32_e32 v17, v17, v172
	v_mul_f32_e32 v158, v158, v162
	v_mul_f32_e32 v18, v18, v172
	v_mul_f32_e32 v159, v159, v163
	v_mul_f32_e32 v19, v19, v172
	v_mul_f32_e32 v16, v16, v156
	v_mul_f32_e32 v17, v17, v157
	v_mul_f32_e32 v18, v18, v158
	v_mul_f32_e32 v19, v19, v159
	v_cvt_pk_bf16_f32 v168, v16, v17
	v_cvt_pk_bf16_f32 v169, v18, v19
	v_lshlrev_b32_e32 v156, 16, v216
	v_and_b32_e32 v157, 0xffff0000, v216
	v_lshlrev_b32_e32 v158, 16, v217
	v_and_b32_e32 v159, 0xffff0000, v217
	v_mul_f32_e32 v160, 0xbfb8aa3b, v156
	v_mul_f32_e32 v161, 0xbfb8aa3b, v157
	v_mul_f32_e32 v162, 0xbfb8aa3b, v158
	v_mul_f32_e32 v163, 0xbfb8aa3b, v159
	v_exp_f32_e32 v160, v160
	v_exp_f32_e32 v161, v161
	v_exp_f32_e32 v162, v162
	v_exp_f32_e32 v163, v163
	s_nop 0
	v_add_f32_e32 v160, 1.0, v160
	v_add_f32_e32 v161, 1.0, v161
	v_add_f32_e32 v162, 1.0, v162
	v_add_f32_e32 v163, 1.0, v163
	v_rcp_f32_e32 v160, v160
	v_rcp_f32_e32 v161, v161
	v_rcp_f32_e32 v162, v162
	v_rcp_f32_e32 v163, v163
	s_nop 0
	v_mul_f32_e32 v156, v156, v160
	v_mul_f32_e32 v20, v20, v172
	v_mul_f32_e32 v157, v157, v161
	v_mul_f32_e32 v21, v21, v172
	v_mul_f32_e32 v158, v158, v162
	v_mul_f32_e32 v22, v22, v172
	v_mul_f32_e32 v159, v159, v163
	v_mul_f32_e32 v23, v23, v172
	v_mul_f32_e32 v20, v20, v156
	v_mul_f32_e32 v21, v21, v157
	v_mul_f32_e32 v22, v22, v158
	v_mul_f32_e32 v23, v23, v159
	v_cvt_pk_bf16_f32 v170, v20, v21
	v_cvt_pk_bf16_f32 v171, v22, v23
	s_add_i32 s5, s41, s54
	s_add_i32 s5, s5, 0
	s_lshl_b32 s5, s5, 17
	s_add_u32 s0, s58, s5
	s_addc_u32 s1, s59, 0
	global_store_dwordx4 v196, v[164:167], s[0:1]
	global_store_dwordx4 v196, v[168:171], s[0:1] offset:16
	s_nop 1
	v_rcp_f32_e32 v172, v76
	v_lshlrev_b32_e32 v156, 16, v218
	v_and_b32_e32 v157, 0xffff0000, v218
	v_lshlrev_b32_e32 v158, 16, v219
	v_and_b32_e32 v159, 0xffff0000, v219
	v_mul_f32_e32 v160, 0xbfb8aa3b, v156
	v_mul_f32_e32 v161, 0xbfb8aa3b, v157
	v_mul_f32_e32 v162, 0xbfb8aa3b, v158
	v_mul_f32_e32 v163, 0xbfb8aa3b, v159
	v_exp_f32_e32 v160, v160
	v_exp_f32_e32 v161, v161
	v_exp_f32_e32 v162, v162
	v_exp_f32_e32 v163, v163
	s_nop 0
	v_add_f32_e32 v160, 1.0, v160
	v_add_f32_e32 v161, 1.0, v161
	v_add_f32_e32 v162, 1.0, v162
	v_add_f32_e32 v163, 1.0, v163
	v_rcp_f32_e32 v160, v160
	v_rcp_f32_e32 v161, v161
	v_rcp_f32_e32 v162, v162
	v_rcp_f32_e32 v163, v163
	s_nop 0
	v_mul_f32_e32 v156, v156, v160
	v_mul_f32_e32 v24, v24, v172
	v_mul_f32_e32 v157, v157, v161
	v_mul_f32_e32 v25, v25, v172
	v_mul_f32_e32 v158, v158, v162
	v_mul_f32_e32 v26, v26, v172
	v_mul_f32_e32 v159, v159, v163
	v_mul_f32_e32 v27, v27, v172
	v_mul_f32_e32 v24, v24, v156
	v_mul_f32_e32 v25, v25, v157
	v_mul_f32_e32 v26, v26, v158
	v_mul_f32_e32 v27, v27, v159
	v_cvt_pk_bf16_f32 v164, v24, v25
	v_cvt_pk_bf16_f32 v165, v26, v27
	v_lshlrev_b32_e32 v156, 16, v220
	v_and_b32_e32 v157, 0xffff0000, v220
	v_lshlrev_b32_e32 v158, 16, v221
	v_and_b32_e32 v159, 0xffff0000, v221
	v_mul_f32_e32 v160, 0xbfb8aa3b, v156
	v_mul_f32_e32 v161, 0xbfb8aa3b, v157
	v_mul_f32_e32 v162, 0xbfb8aa3b, v158
	v_mul_f32_e32 v163, 0xbfb8aa3b, v159
	v_exp_f32_e32 v160, v160
	v_exp_f32_e32 v161, v161
	v_exp_f32_e32 v162, v162
	v_exp_f32_e32 v163, v163
	s_nop 0
	v_add_f32_e32 v160, 1.0, v160
	v_add_f32_e32 v161, 1.0, v161
	v_add_f32_e32 v162, 1.0, v162
	v_add_f32_e32 v163, 1.0, v163
	v_rcp_f32_e32 v160, v160
	v_rcp_f32_e32 v161, v161
	v_rcp_f32_e32 v162, v162
	v_rcp_f32_e32 v163, v163
	s_nop 0
	v_mul_f32_e32 v156, v156, v160
	v_mul_f32_e32 v28, v28, v172
	v_mul_f32_e32 v157, v157, v161
	v_mul_f32_e32 v29, v29, v172
	v_mul_f32_e32 v158, v158, v162
	v_mul_f32_e32 v30, v30, v172
	v_mul_f32_e32 v159, v159, v163
	v_mul_f32_e32 v31, v31, v172
	v_mul_f32_e32 v28, v28, v156
	v_mul_f32_e32 v29, v29, v157
	v_mul_f32_e32 v30, v30, v158
	v_mul_f32_e32 v31, v31, v159
	v_cvt_pk_bf16_f32 v166, v28, v29
	v_cvt_pk_bf16_f32 v167, v30, v31
	v_lshlrev_b32_e32 v156, 16, v222
	v_and_b32_e32 v157, 0xffff0000, v222
	v_lshlrev_b32_e32 v158, 16, v223
	v_and_b32_e32 v159, 0xffff0000, v223
	v_mul_f32_e32 v160, 0xbfb8aa3b, v156
	v_mul_f32_e32 v161, 0xbfb8aa3b, v157
	v_mul_f32_e32 v162, 0xbfb8aa3b, v158
	v_mul_f32_e32 v163, 0xbfb8aa3b, v159
	v_exp_f32_e32 v160, v160
	v_exp_f32_e32 v161, v161
	v_exp_f32_e32 v162, v162
	v_exp_f32_e32 v163, v163
	s_nop 0
	v_add_f32_e32 v160, 1.0, v160
	v_add_f32_e32 v161, 1.0, v161
	v_add_f32_e32 v162, 1.0, v162
	v_add_f32_e32 v163, 1.0, v163
	v_rcp_f32_e32 v160, v160
	v_rcp_f32_e32 v161, v161
	v_rcp_f32_e32 v162, v162
	v_rcp_f32_e32 v163, v163
	s_nop 0
	v_mul_f32_e32 v156, v156, v160
	v_mul_f32_e32 v32, v32, v172
	v_mul_f32_e32 v157, v157, v161
	v_mul_f32_e32 v33, v33, v172
	v_mul_f32_e32 v158, v158, v162
	v_mul_f32_e32 v34, v34, v172
	v_mul_f32_e32 v159, v159, v163
	v_mul_f32_e32 v35, v35, v172
	v_mul_f32_e32 v32, v32, v156
	v_mul_f32_e32 v33, v33, v157
	v_mul_f32_e32 v34, v34, v158
	v_mul_f32_e32 v35, v35, v159
	v_cvt_pk_bf16_f32 v168, v32, v33
	v_cvt_pk_bf16_f32 v169, v34, v35
	v_lshlrev_b32_e32 v156, 16, v224
	v_and_b32_e32 v157, 0xffff0000, v224
	v_lshlrev_b32_e32 v158, 16, v225
	v_and_b32_e32 v159, 0xffff0000, v225
	v_mul_f32_e32 v160, 0xbfb8aa3b, v156
	v_mul_f32_e32 v161, 0xbfb8aa3b, v157
	v_mul_f32_e32 v162, 0xbfb8aa3b, v158
	v_mul_f32_e32 v163, 0xbfb8aa3b, v159
	v_exp_f32_e32 v160, v160
	v_exp_f32_e32 v161, v161
	v_exp_f32_e32 v162, v162
	v_exp_f32_e32 v163, v163
	s_nop 0
	v_add_f32_e32 v160, 1.0, v160
	v_add_f32_e32 v161, 1.0, v161
	v_add_f32_e32 v162, 1.0, v162
	v_add_f32_e32 v163, 1.0, v163
	v_rcp_f32_e32 v160, v160
	v_rcp_f32_e32 v161, v161
	v_rcp_f32_e32 v162, v162
	v_rcp_f32_e32 v163, v163
	s_nop 0
	v_mul_f32_e32 v156, v156, v160
	v_mul_f32_e32 v36, v36, v172
	v_mul_f32_e32 v157, v157, v161
	v_mul_f32_e32 v37, v37, v172
	v_mul_f32_e32 v158, v158, v162
	v_mul_f32_e32 v38, v38, v172
	v_mul_f32_e32 v159, v159, v163
	v_mul_f32_e32 v39, v39, v172
	v_mul_f32_e32 v36, v36, v156
	v_mul_f32_e32 v37, v37, v157
	v_mul_f32_e32 v38, v38, v158
	v_mul_f32_e32 v39, v39, v159
	v_cvt_pk_bf16_f32 v170, v36, v37
	v_cvt_pk_bf16_f32 v171, v38, v39
	s_add_i32 s5, s41, s54
	s_add_i32 s5, s5, 2
	s_lshl_b32 s5, s5, 17
	s_add_u32 s0, s58, s5
	s_addc_u32 s1, s59, 0
	global_store_dwordx4 v196, v[164:167], s[0:1]
	global_store_dwordx4 v196, v[168:171], s[0:1] offset:16
	s_nop 1
	s_waitcnt vmcnt(4)
	v_rcp_f32_e32 v172, v80
	v_lshlrev_b32_e32 v156, 16, v124
	v_and_b32_e32 v157, 0xffff0000, v124
	v_lshlrev_b32_e32 v158, 16, v125
	v_and_b32_e32 v159, 0xffff0000, v125
	v_mul_f32_e32 v160, 0xbfb8aa3b, v156
	v_mul_f32_e32 v161, 0xbfb8aa3b, v157
	v_mul_f32_e32 v162, 0xbfb8aa3b, v158
	v_mul_f32_e32 v163, 0xbfb8aa3b, v159
	v_exp_f32_e32 v160, v160
	v_exp_f32_e32 v161, v161
	v_exp_f32_e32 v162, v162
	v_exp_f32_e32 v163, v163
	s_nop 0
	v_add_f32_e32 v160, 1.0, v160
	v_add_f32_e32 v161, 1.0, v161
	v_add_f32_e32 v162, 1.0, v162
	v_add_f32_e32 v163, 1.0, v163
	v_rcp_f32_e32 v160, v160
	v_rcp_f32_e32 v161, v161
	v_rcp_f32_e32 v162, v162
	v_rcp_f32_e32 v163, v163
	s_nop 0
	v_mul_f32_e32 v156, v156, v160
	v_mul_f32_e32 v40, v40, v172
	v_mul_f32_e32 v157, v157, v161
	v_mul_f32_e32 v41, v41, v172
	v_mul_f32_e32 v158, v158, v162
	v_mul_f32_e32 v42, v42, v172
	v_mul_f32_e32 v159, v159, v163
	v_mul_f32_e32 v43, v43, v172
	v_mul_f32_e32 v40, v40, v156
	v_mul_f32_e32 v41, v41, v157
	v_mul_f32_e32 v42, v42, v158
	v_mul_f32_e32 v43, v43, v159
	v_cvt_pk_bf16_f32 v164, v40, v41
	v_cvt_pk_bf16_f32 v165, v42, v43
	v_lshlrev_b32_e32 v156, 16, v126
	v_and_b32_e32 v157, 0xffff0000, v126
	v_lshlrev_b32_e32 v158, 16, v127
	v_and_b32_e32 v159, 0xffff0000, v127
	v_mul_f32_e32 v160, 0xbfb8aa3b, v156
	v_mul_f32_e32 v161, 0xbfb8aa3b, v157
	v_mul_f32_e32 v162, 0xbfb8aa3b, v158
	v_mul_f32_e32 v163, 0xbfb8aa3b, v159
	v_exp_f32_e32 v160, v160
	v_exp_f32_e32 v161, v161
	v_exp_f32_e32 v162, v162
	v_exp_f32_e32 v163, v163
	s_nop 0
	v_add_f32_e32 v160, 1.0, v160
	v_add_f32_e32 v161, 1.0, v161
	v_add_f32_e32 v162, 1.0, v162
	v_add_f32_e32 v163, 1.0, v163
	v_rcp_f32_e32 v160, v160
	v_rcp_f32_e32 v161, v161
	v_rcp_f32_e32 v162, v162
	v_rcp_f32_e32 v163, v163
	s_nop 0
	v_mul_f32_e32 v156, v156, v160
	v_mul_f32_e32 v44, v44, v172
	v_mul_f32_e32 v157, v157, v161
	v_mul_f32_e32 v45, v45, v172
	v_mul_f32_e32 v158, v158, v162
	v_mul_f32_e32 v46, v46, v172
	v_mul_f32_e32 v159, v159, v163
	v_mul_f32_e32 v47, v47, v172
	v_mul_f32_e32 v44, v44, v156
	v_mul_f32_e32 v45, v45, v157
	v_mul_f32_e32 v46, v46, v158
	v_mul_f32_e32 v47, v47, v159
	v_cvt_pk_bf16_f32 v166, v44, v45
	v_cvt_pk_bf16_f32 v167, v46, v47
	v_lshlrev_b32_e32 v156, 16, v128
	v_and_b32_e32 v157, 0xffff0000, v128
	v_lshlrev_b32_e32 v158, 16, v129
	v_and_b32_e32 v159, 0xffff0000, v129
	v_mul_f32_e32 v160, 0xbfb8aa3b, v156
	v_mul_f32_e32 v161, 0xbfb8aa3b, v157
	v_mul_f32_e32 v162, 0xbfb8aa3b, v158
	v_mul_f32_e32 v163, 0xbfb8aa3b, v159
	v_exp_f32_e32 v160, v160
	v_exp_f32_e32 v161, v161
	v_exp_f32_e32 v162, v162
	v_exp_f32_e32 v163, v163
	s_nop 0
	v_add_f32_e32 v160, 1.0, v160
	v_add_f32_e32 v161, 1.0, v161
	v_add_f32_e32 v162, 1.0, v162
	v_add_f32_e32 v163, 1.0, v163
	v_rcp_f32_e32 v160, v160
	v_rcp_f32_e32 v161, v161
	v_rcp_f32_e32 v162, v162
	v_rcp_f32_e32 v163, v163
	s_nop 0
	v_mul_f32_e32 v156, v156, v160
	v_mul_f32_e32 v48, v48, v172
	v_mul_f32_e32 v157, v157, v161
	v_mul_f32_e32 v49, v49, v172
	v_mul_f32_e32 v158, v158, v162
	v_mul_f32_e32 v50, v50, v172
	v_mul_f32_e32 v159, v159, v163
	v_mul_f32_e32 v51, v51, v172
	v_mul_f32_e32 v48, v48, v156
	v_mul_f32_e32 v49, v49, v157
	v_mul_f32_e32 v50, v50, v158
	v_mul_f32_e32 v51, v51, v159
	v_cvt_pk_bf16_f32 v168, v48, v49
	v_cvt_pk_bf16_f32 v169, v50, v51
	v_lshlrev_b32_e32 v156, 16, v130
	v_and_b32_e32 v157, 0xffff0000, v130
	v_lshlrev_b32_e32 v158, 16, v131
	v_and_b32_e32 v159, 0xffff0000, v131
	v_mul_f32_e32 v160, 0xbfb8aa3b, v156
	v_mul_f32_e32 v161, 0xbfb8aa3b, v157
	v_mul_f32_e32 v162, 0xbfb8aa3b, v158
	v_mul_f32_e32 v163, 0xbfb8aa3b, v159
	v_exp_f32_e32 v160, v160
	v_exp_f32_e32 v161, v161
	v_exp_f32_e32 v162, v162
	v_exp_f32_e32 v163, v163
	s_nop 0
	v_add_f32_e32 v160, 1.0, v160
	v_add_f32_e32 v161, 1.0, v161
	v_add_f32_e32 v162, 1.0, v162
	v_add_f32_e32 v163, 1.0, v163
	v_rcp_f32_e32 v160, v160
	v_rcp_f32_e32 v161, v161
	v_rcp_f32_e32 v162, v162
	v_rcp_f32_e32 v163, v163
	s_nop 0
	v_mul_f32_e32 v156, v156, v160
	v_mul_f32_e32 v52, v52, v172
	v_mul_f32_e32 v157, v157, v161
	v_mul_f32_e32 v53, v53, v172
	v_mul_f32_e32 v158, v158, v162
	v_mul_f32_e32 v54, v54, v172
	v_mul_f32_e32 v159, v159, v163
	v_mul_f32_e32 v55, v55, v172
	v_mul_f32_e32 v52, v52, v156
	v_mul_f32_e32 v53, v53, v157
	v_mul_f32_e32 v54, v54, v158
	v_mul_f32_e32 v55, v55, v159
	v_cvt_pk_bf16_f32 v170, v52, v53
	v_cvt_pk_bf16_f32 v171, v54, v55
	s_add_i32 s5, s41, s54
	s_add_i32 s5, s5, 4
	s_lshl_b32 s5, s5, 17
	s_add_u32 s0, s58, s5
	s_addc_u32 s1, s59, 0
	global_store_dwordx4 v196, v[164:167], s[0:1]
	global_store_dwordx4 v196, v[168:171], s[0:1] offset:16
	s_nop 1
	v_rcp_f32_e32 v172, v84
	v_lshlrev_b32_e32 v156, 16, v132
	v_and_b32_e32 v157, 0xffff0000, v132
	v_lshlrev_b32_e32 v158, 16, v133
	v_and_b32_e32 v159, 0xffff0000, v133
	v_mul_f32_e32 v160, 0xbfb8aa3b, v156
	v_mul_f32_e32 v161, 0xbfb8aa3b, v157
	v_mul_f32_e32 v162, 0xbfb8aa3b, v158
	v_mul_f32_e32 v163, 0xbfb8aa3b, v159
	v_exp_f32_e32 v160, v160
	v_exp_f32_e32 v161, v161
	v_exp_f32_e32 v162, v162
	v_exp_f32_e32 v163, v163
	s_nop 0
	v_add_f32_e32 v160, 1.0, v160
	v_add_f32_e32 v161, 1.0, v161
	v_add_f32_e32 v162, 1.0, v162
	v_add_f32_e32 v163, 1.0, v163
	v_rcp_f32_e32 v160, v160
	v_rcp_f32_e32 v161, v161
	v_rcp_f32_e32 v162, v162
	v_rcp_f32_e32 v163, v163
	s_nop 0
	v_mul_f32_e32 v156, v156, v160
	v_mul_f32_e32 v56, v56, v172
	v_mul_f32_e32 v157, v157, v161
	v_mul_f32_e32 v57, v57, v172
	v_mul_f32_e32 v158, v158, v162
	v_mul_f32_e32 v58, v58, v172
	v_mul_f32_e32 v159, v159, v163
	v_mul_f32_e32 v59, v59, v172
	v_mul_f32_e32 v56, v56, v156
	v_mul_f32_e32 v57, v57, v157
	v_mul_f32_e32 v58, v58, v158
	v_mul_f32_e32 v59, v59, v159
	v_cvt_pk_bf16_f32 v164, v56, v57
	v_cvt_pk_bf16_f32 v165, v58, v59
	v_lshlrev_b32_e32 v156, 16, v134
	v_and_b32_e32 v157, 0xffff0000, v134
	v_lshlrev_b32_e32 v158, 16, v135
	v_and_b32_e32 v159, 0xffff0000, v135
	v_mul_f32_e32 v160, 0xbfb8aa3b, v156
	v_mul_f32_e32 v161, 0xbfb8aa3b, v157
	v_mul_f32_e32 v162, 0xbfb8aa3b, v158
	v_mul_f32_e32 v163, 0xbfb8aa3b, v159
	v_exp_f32_e32 v160, v160
	v_exp_f32_e32 v161, v161
	v_exp_f32_e32 v162, v162
	v_exp_f32_e32 v163, v163
	s_nop 0
	v_add_f32_e32 v160, 1.0, v160
	v_add_f32_e32 v161, 1.0, v161
	v_add_f32_e32 v162, 1.0, v162
	v_add_f32_e32 v163, 1.0, v163
	v_rcp_f32_e32 v160, v160
	v_rcp_f32_e32 v161, v161
	v_rcp_f32_e32 v162, v162
	v_rcp_f32_e32 v163, v163
	s_nop 0
	v_mul_f32_e32 v156, v156, v160
	v_mul_f32_e32 v60, v60, v172
	v_mul_f32_e32 v157, v157, v161
	v_mul_f32_e32 v61, v61, v172
	v_mul_f32_e32 v158, v158, v162
	v_mul_f32_e32 v62, v62, v172
	v_mul_f32_e32 v159, v159, v163
	v_mul_f32_e32 v63, v63, v172
	v_mul_f32_e32 v60, v60, v156
	v_mul_f32_e32 v61, v61, v157
	v_mul_f32_e32 v62, v62, v158
	v_mul_f32_e32 v63, v63, v159
	v_cvt_pk_bf16_f32 v166, v60, v61
	v_cvt_pk_bf16_f32 v167, v62, v63
	v_lshlrev_b32_e32 v156, 16, v136
	v_and_b32_e32 v157, 0xffff0000, v136
	v_lshlrev_b32_e32 v158, 16, v137
	v_and_b32_e32 v159, 0xffff0000, v137
	v_mul_f32_e32 v160, 0xbfb8aa3b, v156
	v_mul_f32_e32 v161, 0xbfb8aa3b, v157
	v_mul_f32_e32 v162, 0xbfb8aa3b, v158
	v_mul_f32_e32 v163, 0xbfb8aa3b, v159
	v_exp_f32_e32 v160, v160
	v_exp_f32_e32 v161, v161
	v_exp_f32_e32 v162, v162
	v_exp_f32_e32 v163, v163
	s_nop 0
	v_add_f32_e32 v160, 1.0, v160
	v_add_f32_e32 v161, 1.0, v161
	v_add_f32_e32 v162, 1.0, v162
	v_add_f32_e32 v163, 1.0, v163
	v_rcp_f32_e32 v160, v160
	v_rcp_f32_e32 v161, v161
	v_rcp_f32_e32 v162, v162
	v_rcp_f32_e32 v163, v163
	s_nop 0
	v_mul_f32_e32 v156, v156, v160
	v_mul_f32_e32 v64, v64, v172
	v_mul_f32_e32 v157, v157, v161
	v_mul_f32_e32 v65, v65, v172
	v_mul_f32_e32 v158, v158, v162
	v_mul_f32_e32 v66, v66, v172
	v_mul_f32_e32 v159, v159, v163
	v_mul_f32_e32 v67, v67, v172
	v_mul_f32_e32 v64, v64, v156
	v_mul_f32_e32 v65, v65, v157
	v_mul_f32_e32 v66, v66, v158
	v_mul_f32_e32 v67, v67, v159
	v_cvt_pk_bf16_f32 v168, v64, v65
	v_cvt_pk_bf16_f32 v169, v66, v67
	v_lshlrev_b32_e32 v156, 16, v138
	v_and_b32_e32 v157, 0xffff0000, v138
	v_lshlrev_b32_e32 v158, 16, v139
	v_and_b32_e32 v159, 0xffff0000, v139
	v_mul_f32_e32 v160, 0xbfb8aa3b, v156
	v_mul_f32_e32 v161, 0xbfb8aa3b, v157
	v_mul_f32_e32 v162, 0xbfb8aa3b, v158
	v_mul_f32_e32 v163, 0xbfb8aa3b, v159
	v_exp_f32_e32 v160, v160
	v_exp_f32_e32 v161, v161
	v_exp_f32_e32 v162, v162
	v_exp_f32_e32 v163, v163
	s_nop 0
	v_add_f32_e32 v160, 1.0, v160
	v_add_f32_e32 v161, 1.0, v161
	v_add_f32_e32 v162, 1.0, v162
	v_add_f32_e32 v163, 1.0, v163
	v_rcp_f32_e32 v160, v160
	v_rcp_f32_e32 v161, v161
	v_rcp_f32_e32 v162, v162
	v_rcp_f32_e32 v163, v163
	s_nop 0
	v_mul_f32_e32 v156, v156, v160
	v_mul_f32_e32 v68, v68, v172
	v_mul_f32_e32 v157, v157, v161
	v_mul_f32_e32 v69, v69, v172
	v_mul_f32_e32 v158, v158, v162
	v_mul_f32_e32 v70, v70, v172
	v_mul_f32_e32 v159, v159, v163
	v_mul_f32_e32 v71, v71, v172
	v_mul_f32_e32 v68, v68, v156
	v_mul_f32_e32 v69, v69, v157
	v_mul_f32_e32 v70, v70, v158
	v_mul_f32_e32 v71, v71, v159
	v_cvt_pk_bf16_f32 v170, v68, v69
	v_cvt_pk_bf16_f32 v171, v70, v71
	s_add_i32 s5, s41, s54
	s_add_i32 s5, s5, 6
	s_lshl_b32 s5, s5, 17
	s_add_u32 s0, s58, s5
	s_addc_u32 s1, s59, 0
	global_store_dwordx4 v196, v[164:167], s[0:1]
	global_store_dwordx4 v196, v[168:171], s[0:1] offset:16
	s_nop 1
.La0_exit:
	v_readlane_b32 s56, v255, 8
	v_readlane_b32 s57, v255, 9
.LBB0_330:
	s_waitcnt vmcnt(0)
	s_barrier
	s_mov_b64 s[0:1], exec
	v_readlane_b32 s4, v255, 6
	v_readlane_b32 s5, v255, 7
	s_and_b64 s[4:5], s[0:1], s[4:5]
	s_mov_b64 exec, s[4:5]
	s_cbranch_execz .LBB0_382
	s_add_i32 s6, 0, 0x27e28
	s_mov_b64 s[4:5], s[56:57]
	v_mov_b32_e32 v1, s6
	s_add_i32 s6, 0, 0x27e20
	ds_read_b32 v2, v1
	v_mov_b32_e32 v1, s6
	s_waitcnt vmcnt(0) expcnt(0) lgkmcnt(0)
	ds_read_b32 v3, v1
	s_add_i32 s6, 0, 0x27e24
	v_mov_b32_e32 v1, s6
	ds_read_b32 v1, v1
	v_readfirstlane_b32 s12, v2
	s_waitcnt lgkmcnt(1)
	v_cmp_ne_u32_e32 vcc, 0, v3
	s_cbranch_vccnz .LBB0_346
	v_readlane_b32 s6, v255, 4
	v_readlane_b32 s7, v255, 5
	s_load_dwordx2 s[10:11], s[6:7], 0x4
	s_add_u32 s6, s4, 0x1000
	s_addc_u32 s7, s5, 0
	s_add_u32 s8, s4, 0x1100
	s_addc_u32 s9, s5, 0
	s_waitcnt lgkmcnt(0)
	s_mul_i32 s13, s10, s33
	s_add_u32 s10, s4, 0x1200
	s_mul_i32 s13, s13, s11
	s_addc_u32 s11, s5, 0
	s_add_u32 s20, s4, 0x1300
	s_addc_u32 s21, s5, 0
	s_mov_b32 s14, 1
	v_mov_b32_e32 v17, 0
	s_branch .LBB0_334

	.amdhsa_kernel _Z14fwd_megakernel4Args
		.amdhsa_group_segment_fixed_size 0
		.amdhsa_private_segment_fixed_size 0
		.amdhsa_kernarg_size 344
		.amdhsa_user_sgpr_count 2
		.amdhsa_user_sgpr_dispatch_ptr 0
		.amdhsa_user_sgpr_queue_ptr 0
		.amdhsa_user_sgpr_kernarg_segment_ptr 1
		.amdhsa_user_sgpr_dispatch_id 0
		.amdhsa_user_sgpr_kernarg_preload_length 0
		.amdhsa_user_sgpr_kernarg_preload_offset 0
		.amdhsa_user_sgpr_private_segment_size 0
		.amdhsa_uses_dynamic_stack 0
		.amdhsa_enable_private_segment 0
		.amdhsa_system_sgpr_workgroup_id_x 1
		.amdhsa_system_sgpr_workgroup_id_y 0
		.amdhsa_system_sgpr_workgroup_id_z 0
		.amdhsa_system_sgpr_workgroup_info 0
		.amdhsa_system_vgpr_workitem_id 0
		.amdhsa_next_free_vgpr 256
		.amdhsa_next_free_sgpr 102
		.amdhsa_accum_offset 256
		.amdhsa_reserve_vcc 1
		.amdhsa_float_round_mode_32 0
		.amdhsa_float_round_mode_16_64 0
		.amdhsa_float_denorm_mode_32 3
		.amdhsa_float_denorm_mode_16_64 3
		.amdhsa_dx10_clamp 1
		.amdhsa_ieee_mode 1
		.amdhsa_fp16_overflow 0
		.amdhsa_tg_split 0
		.amdhsa_exception_fp_ieee_invalid_op 0
		.amdhsa_exception_fp_denorm_src 0
		.amdhsa_exception_fp_ieee_div_zero 0
		.amdhsa_exception_fp_ieee_overflow 0
		.amdhsa_exception_fp_ieee_underflow 0
		.amdhsa_exception_fp_ieee_inexact 0
		.amdhsa_exception_int_div_zero 0
	.end_amdhsa_kernel

amdhsa.kernels:
  - .agpr_count:     0
    .args:
      - .offset:         0
        .size:           88
        .value_kind:     by_value
      - .offset:         88
        .size:           4
        .value_kind:     hidden_block_count_x
      - .offset:         92
        .size:           4
        .value_kind:     hidden_block_count_y
      - .offset:         96
        .size:           4
        .value_kind:     hidden_block_count_z
      - .offset:         100
        .size:           2
        .value_kind:     hidden_group_size_x
      - .offset:         102
        .size:           2
        .value_kind:     hidden_group_size_y
      - .offset:         104
        .size:           2
        .value_kind:     hidden_group_size_z
      - .offset:         106
        .size:           2
        .value_kind:     hidden_remainder_x
      - .offset:         108
        .size:           2
        .value_kind:     hidden_remainder_y
      - .offset:         110
        .size:           2
        .value_kind:     hidden_remainder_z
      - .offset:         128
        .size:           8
        .value_kind:     hidden_global_offset_x
      - .offset:         136
        .size:           8
        .value_kind:     hidden_global_offset_y
      - .offset:         144
        .size:           8
        .value_kind:     hidden_global_offset_z
      - .offset:         152
        .size:           2
        .value_kind:     hidden_grid_dims
      - .offset:         208
        .size:           4
        .value_kind:     hidden_dynamic_lds_size
    .group_segment_fixed_size: 0
    .kernarg_segment_align: 8
    .kernarg_segment_size: 344
    .language:       OpenCL C
    .language_version:
      - 2
      - 0
    .max_flat_workgroup_size: 512
    .name:           _Z14fwd_megakernel4Args
    .private_segment_fixed_size: 0
    .sgpr_count:     108
    .sgpr_spill_count: 46
    .symbol:         _Z14fwd_megakernel4Args.kd
    .uniform_work_group_size: 1
    .uses_dynamic_stack: false
    .vgpr_count:     256
    .vgpr_spill_count: 0
    .wavefront_size: 64
